# selected-branch diagonal tile in place with integer masks; cross-lane row max via v_permlane16/32_swap instead of two ds_bpermute round trips
# speedup vs baseline: 1.0270x; 1.0021x over previous
.LBB0_255:
	s_or_b32 s16, s44, s23
	s_cmp_gt_i32 s16, s18
	s_cbranch_scc1 .LBB0_254
	s_lshl_b32 s16, s16, 14
	s_and_b32 s16, s16, 0xc000
	s_add_i32 s16, s16, 0
	s_waitcnt lgkmcnt(0)
	v_add_u32_e32 v50, s16, v215
	v_and_b32_e32 v51, 64, v147
	v_add_u32_e32 v232, v50, v213
	v_add_u32_e32 v82, 64, v51
	v_add_u32_e32 v165, v50, v214
	ds_read_b128 v[70:73], v232 offset:32768
	ds_read_b128 v[74:77], v232 offset:34816
	ds_read_b128 v[78:81], v165 offset:32768
	ds_read_b128 v[66:69], v165 offset:34816
	ds_read_b128 v[62:65], v232 offset:36864
	ds_read_b128 v[54:57], v232 offset:38912
	ds_read_b128 v[58:61], v165 offset:36864
	ds_read_b128 v[50:53], v165 offset:38912
	s_add_i32 s42, s44, s71
	s_lshl_b32 s82, s42, 6
	s_or_b32 s42, s82, 63
	s_cmp_le_u32 s42, s5
	v_xor_b32_e32 v0, 16, v147
	s_cselect_b64 s[42:43], -1, 0
	s_cmp_gt_i32 s82, s19
	v_cmp_lt_i32_e32 vcc, v0, v82
	v_xor_b32_e32 v83, 32, v147
	s_cselect_b64 s[44:45], -1, 0
	v_cndmask_b32_e32 v0, v147, v0, vcc
	v_cmp_lt_i32_e32 vcc, v83, v82
	s_and_b64 s[42:43], s[42:43], s[44:45]
	v_lshlrev_b32_e32 v0, 2, v0
	v_cndmask_b32_e32 v82, v147, v83, vcc
	v_lshlrev_b32_e32 v149, 2, v82
	s_andn2_b64 vcc, exec, s[42:43]
	s_mov_b64 s[42:43], -1
	s_cbranch_vccz .Lsw_p1
	v_lshl_add_u32 v114, s82, 2, v145
	ds_read2_b32 v[82:83], v114 offset0:127 offset1:128
	ds_read2_b32 v[84:85], v114 offset0:129 offset1:130
	ds_read2_b32 v[86:87], v114 offset0:143 offset1:144
	ds_read2_b32 v[88:89], v114 offset0:145 offset1:146
	s_waitcnt lgkmcnt(4)
	v_mfma_f32_16x16x32_bf16 v[70:73], v[70:73], v[2:5], 0
	v_mfma_f32_16x16x32_bf16 v[74:77], v[74:77], v[2:5], 0
	v_mfma_f32_16x16x32_bf16 v[62:65], v[62:65], v[2:5], 0
	v_mfma_f32_16x16x32_bf16 v[54:57], v[54:57], v[2:5], 0
	ds_read2_b32 v[90:91], v114 offset0:159 offset1:160
	ds_read2_b32 v[92:93], v114 offset0:161 offset1:162
	ds_read2_b32 v[94:95], v114 offset0:175 offset1:176
	ds_read2_b32 v[96:97], v114 offset0:177 offset1:178
	v_mfma_f32_16x16x32_bf16 v[70:73], v[78:81], v[6:9], v[70:73]
	v_mfma_f32_16x16x32_bf16 v[74:77], v[66:69], v[6:9], v[74:77]
	v_mfma_f32_16x16x32_bf16 v[62:65], v[58:61], v[6:9], v[62:65]
	v_mfma_f32_16x16x32_bf16 v[54:57], v[50:53], v[6:9], v[54:57]
	s_waitcnt lgkmcnt(0)
	ds_read_b128 v[98:101], v232 offset:32768
	ds_read_b128 v[78:81], v165 offset:32768
	ds_read_b128 v[102:105], v232 offset:34816
	ds_read_b128 v[66:69], v165 offset:34816
	ds_read_b128 v[106:109], v232 offset:36864
	ds_read_b128 v[58:61], v165 offset:36864
	ds_read_b128 v[110:113], v232 offset:38912
	ds_read_b128 v[50:53], v165 offset:38912
	v_pk_fma_f32 v[70:71], v[70:71], s[36:37], v[82:83] op_sel_hi:[1,0,1]
	v_pk_fma_f32 v[72:73], v[72:73], s[36:37], v[84:85] op_sel_hi:[1,0,1]
	v_pk_fma_f32 v[74:75], v[74:75], s[36:37], v[86:87] op_sel_hi:[1,0,1]
	v_pk_fma_f32 v[76:77], v[76:77], s[36:37], v[88:89] op_sel_hi:[1,0,1]
	v_pk_fma_f32 v[62:63], v[62:63], s[36:37], v[90:91] op_sel_hi:[1,0,1]
	v_pk_fma_f32 v[64:65], v[64:65], s[36:37], v[92:93] op_sel_hi:[1,0,1]
	v_pk_fma_f32 v[54:55], v[54:55], s[36:37], v[94:95] op_sel_hi:[1,0,1]
	v_pk_fma_f32 v[56:57], v[56:57], s[36:37], v[96:97] op_sel_hi:[1,0,1]
	v_or_b32_e32 v117, s82, v216
	v_sub_u32_e32 v115, v144, v117
	v_subrev_u32_e32 v117, 0, v115
	v_cmp_gt_u32_e64 s[48:49], s26, v117
	v_subrev_u32_e32 v117, 1, v115
	v_cmp_gt_u32_e64 s[50:51], s26, v117
	v_subrev_u32_e32 v117, 2, v115
	v_cmp_gt_u32_e64 s[52:53], s26, v117
	v_subrev_u32_e32 v117, 3, v115
	v_cmp_gt_u32_e64 s[54:55], s26, v117
	v_subrev_u32_e32 v117, 16, v115
	v_cmp_gt_u32_e64 s[56:57], s26, v117
	v_subrev_u32_e32 v117, 17, v115
	v_cmp_gt_u32_e64 s[58:59], s26, v117
	v_subrev_u32_e32 v117, 18, v115
	v_cmp_gt_u32_e64 s[60:61], s26, v117
	v_subrev_u32_e32 v117, 19, v115
	v_cmp_gt_u32_e64 s[62:63], s26, v117
	v_cndmask_b32_e64 v70, v148, v70, s[48:49]
	v_cndmask_b32_e64 v71, v148, v71, s[50:51]
	v_cndmask_b32_e64 v72, v148, v72, s[52:53]
	v_cndmask_b32_e64 v73, v148, v73, s[54:55]
	v_cndmask_b32_e64 v74, v148, v74, s[56:57]
	v_cndmask_b32_e64 v75, v148, v75, s[58:59]
	v_cndmask_b32_e64 v76, v148, v76, s[60:61]
	v_cndmask_b32_e64 v77, v148, v77, s[62:63]
	v_subrev_u32_e32 v117, 32, v115
	v_cmp_gt_u32_e64 s[48:49], s26, v117
	v_subrev_u32_e32 v117, 33, v115
	v_cmp_gt_u32_e64 s[50:51], s26, v117
	v_subrev_u32_e32 v117, 34, v115
	v_cmp_gt_u32_e64 s[52:53], s26, v117
	v_subrev_u32_e32 v117, 35, v115
	v_cmp_gt_u32_e64 s[54:55], s26, v117
	v_subrev_u32_e32 v117, 48, v115
	v_cmp_gt_u32_e64 s[56:57], s26, v117
	v_subrev_u32_e32 v117, 49, v115
	v_cmp_gt_u32_e64 s[58:59], s26, v117
	v_subrev_u32_e32 v117, 50, v115
	v_cmp_gt_u32_e64 s[60:61], s26, v117
	v_subrev_u32_e32 v117, 51, v115
	v_cmp_gt_u32_e64 s[62:63], s26, v117
	v_cndmask_b32_e64 v62, v148, v62, s[48:49]
	v_cndmask_b32_e64 v63, v148, v63, s[50:51]
	v_cndmask_b32_e64 v64, v148, v64, s[52:53]
	v_cndmask_b32_e64 v65, v148, v65, s[54:55]
	v_cndmask_b32_e64 v54, v148, v54, s[56:57]
	v_cndmask_b32_e64 v55, v148, v55, s[58:59]
	v_cndmask_b32_e64 v56, v148, v56, s[60:61]
	v_cndmask_b32_e64 v57, v148, v57, s[62:63]
	v_max3_f32 v116, v70, v71, v72
	v_max3_f32 v116, v116, v73, v74
	v_max3_f32 v116, v116, v75, v76
	v_max3_f32 v116, v116, v77, v62
	v_max3_f32 v116, v116, v63, v64
	v_max3_f32 v116, v116, v65, v54
	v_max3_f32 v116, v116, v55, v56
	v_max3_f32 v116, v116, v57, s29
	v_mov_b32_e32 v117, v116
	s_nop 1
	v_permlane16_swap_b32_e32 v116, v117
	v_max_f32_e32 v116, v116, v117
	v_mov_b32_e32 v117, v116
	s_nop 1
	v_permlane32_swap_b32_e32 v116, v117
	v_max_f32_e32 v116, v116, v117
	v_max_f32_e32 v121, v166, v116
	v_sub_f32_e32 v118, v166, v121
	v_cmp_lt_f32_e32 vcc, s30, v121
	v_exp_f32_e32 v118, v118
	v_mov_b32_e32 v166, v121
	v_cndmask_b32_e32 v120, 0, v121, vcc
	v_pk_mul_f32 v[46:47], v[46:47], v[118:119] op_sel_hi:[1,0]
	v_pk_mul_f32 v[48:49], v[48:49], v[118:119] op_sel_hi:[1,0]
	v_pk_mul_f32 v[42:43], v[42:43], v[118:119] op_sel_hi:[1,0]
	v_pk_mul_f32 v[44:45], v[44:45], v[118:119] op_sel_hi:[1,0]
	v_pk_mul_f32 v[38:39], v[38:39], v[118:119] op_sel_hi:[1,0]
	v_pk_mul_f32 v[40:41], v[40:41], v[118:119] op_sel_hi:[1,0]
	v_pk_mul_f32 v[34:35], v[34:35], v[118:119] op_sel_hi:[1,0]
	v_pk_mul_f32 v[36:37], v[36:37], v[118:119] op_sel_hi:[1,0]
	v_pk_add_f32 v[70:71], v[70:71], v[120:121] op_sel_hi:[1,0] neg_lo:[0,1] neg_hi:[0,1]
	v_pk_add_f32 v[72:73], v[72:73], v[120:121] op_sel_hi:[1,0] neg_lo:[0,1] neg_hi:[0,1]
	v_pk_add_f32 v[74:75], v[74:75], v[120:121] op_sel_hi:[1,0] neg_lo:[0,1] neg_hi:[0,1]
	v_pk_add_f32 v[76:77], v[76:77], v[120:121] op_sel_hi:[1,0] neg_lo:[0,1] neg_hi:[0,1]
	v_pk_add_f32 v[62:63], v[62:63], v[120:121] op_sel_hi:[1,0] neg_lo:[0,1] neg_hi:[0,1]
	v_pk_add_f32 v[64:65], v[64:65], v[120:121] op_sel_hi:[1,0] neg_lo:[0,1] neg_hi:[0,1]
	v_pk_add_f32 v[54:55], v[54:55], v[120:121] op_sel_hi:[1,0] neg_lo:[0,1] neg_hi:[0,1]
	v_pk_add_f32 v[56:57], v[56:57], v[120:121] op_sel_hi:[1,0] neg_lo:[0,1] neg_hi:[0,1]
	v_exp_f32_e32 v70, v70
	v_exp_f32_e32 v71, v71
	v_exp_f32_e32 v72, v72
	v_exp_f32_e32 v73, v73
	v_exp_f32_e32 v74, v74
	v_exp_f32_e32 v75, v75
	v_exp_f32_e32 v76, v76
	v_exp_f32_e32 v77, v77
	v_exp_f32_e32 v62, v62
	v_exp_f32_e32 v63, v63
	v_exp_f32_e32 v64, v64
	v_exp_f32_e32 v65, v65
	v_exp_f32_e32 v54, v54
	v_exp_f32_e32 v55, v55
	v_exp_f32_e32 v56, v56
	v_exp_f32_e32 v57, v57
	s_nop 0
	v_pk_add_f32 v[82:83], v[70:71], v[72:73]
	v_pk_add_f32 v[84:85], v[74:75], v[76:77]
	v_pk_add_f32 v[86:87], v[62:63], v[64:65]
	v_pk_add_f32 v[88:89], v[54:55], v[56:57]
	v_pk_add_f32 v[82:83], v[82:83], v[84:85]
	v_pk_add_f32 v[86:87], v[86:87], v[88:89]
	s_nop 0
	v_pk_add_f32 v[82:83], v[82:83], v[86:87]
	s_nop 0
	v_add_f32_e32 v82, v82, v83
	v_fma_f32 v158, v158, v118, v82
	v_cvt_pk_bf16_f32 v77, v76, v77
	v_cvt_pk_bf16_f32 v76, v74, v75
	v_cvt_pk_bf16_f32 v75, v72, v73
	v_cvt_pk_bf16_f32 v74, v70, v71
	v_cvt_pk_bf16_f32 v62, v62, v63
	v_cvt_pk_bf16_f32 v63, v64, v65
	v_cvt_pk_bf16_f32 v64, v54, v55
	v_cvt_pk_bf16_f32 v65, v56, v57
	s_waitcnt lgkmcnt(0)
	ds_read2_b32 v[82:83], v114 offset0:111 offset1:112
	ds_read2_b32 v[84:85], v114 offset0:113 offset1:114
	ds_read2_b32 v[86:87], v114 offset0:127 offset1:128
	ds_read2_b32 v[88:89], v114 offset0:129 offset1:130
	ds_read2_b32 v[90:91], v114 offset0:143 offset1:144
	ds_read2_b32 v[92:93], v114 offset0:145 offset1:146
	ds_read2_b32 v[94:95], v114 offset0:159 offset1:160
	ds_read2_b32 v[96:97], v114 offset0:161 offset1:162
	v_mfma_f32_16x16x32_bf16 v[98:101], v[98:101], v[10:13], 0
	v_mfma_f32_16x16x32_bf16 v[102:105], v[102:105], v[10:13], 0
	v_mfma_f32_16x16x32_bf16 v[106:109], v[106:109], v[10:13], 0
	v_mfma_f32_16x16x32_bf16 v[110:113], v[110:113], v[10:13], 0
	v_mfma_f32_16x16x32_bf16 v[98:101], v[78:81], v[14:17], v[98:101]
	v_mfma_f32_16x16x32_bf16 v[102:105], v[66:69], v[14:17], v[102:105]
	v_mfma_f32_16x16x32_bf16 v[106:109], v[58:61], v[14:17], v[106:109]
	v_mfma_f32_16x16x32_bf16 v[110:113], v[50:53], v[14:17], v[110:113]
	s_waitcnt lgkmcnt(0)
	s_nop 6
	v_pk_fma_f32 v[98:99], v[98:99], s[36:37], v[82:83] op_sel_hi:[1,0,1]
	v_pk_fma_f32 v[100:101], v[100:101], s[36:37], v[84:85] op_sel_hi:[1,0,1]
	v_pk_fma_f32 v[102:103], v[102:103], s[36:37], v[86:87] op_sel_hi:[1,0,1]
	v_pk_fma_f32 v[104:105], v[104:105], s[36:37], v[88:89] op_sel_hi:[1,0,1]
	v_pk_fma_f32 v[106:107], v[106:107], s[36:37], v[90:91] op_sel_hi:[1,0,1]
	v_pk_fma_f32 v[108:109], v[108:109], s[36:37], v[92:93] op_sel_hi:[1,0,1]
	v_pk_fma_f32 v[110:111], v[110:111], s[36:37], v[94:95] op_sel_hi:[1,0,1]
	v_pk_fma_f32 v[112:113], v[112:113], s[36:37], v[96:97] op_sel_hi:[1,0,1]
	v_or_b32_e32 v117, s82, v216
	v_sub_u32_e32 v115, v144, v117
	v_add_u32_e32 v115, 16, v115
	v_subrev_u32_e32 v117, 0, v115
	v_cmp_gt_u32_e64 s[48:49], s26, v117
	v_subrev_u32_e32 v117, 1, v115
	v_cmp_gt_u32_e64 s[50:51], s26, v117
	v_subrev_u32_e32 v117, 2, v115
	v_cmp_gt_u32_e64 s[52:53], s26, v117
	v_subrev_u32_e32 v117, 3, v115
	v_cmp_gt_u32_e64 s[54:55], s26, v117
	v_subrev_u32_e32 v117, 16, v115
	v_cmp_gt_u32_e64 s[56:57], s26, v117
	v_subrev_u32_e32 v117, 17, v115
	v_cmp_gt_u32_e64 s[58:59], s26, v117
	v_subrev_u32_e32 v117, 18, v115
	v_cmp_gt_u32_e64 s[60:61], s26, v117
	v_subrev_u32_e32 v117, 19, v115
	v_cmp_gt_u32_e64 s[62:63], s26, v117
	v_cndmask_b32_e64 v98, v148, v98, s[48:49]
	v_cndmask_b32_e64 v99, v148, v99, s[50:51]
	v_cndmask_b32_e64 v100, v148, v100, s[52:53]
	v_cndmask_b32_e64 v101, v148, v101, s[54:55]
	v_cndmask_b32_e64 v102, v148, v102, s[56:57]
	v_cndmask_b32_e64 v103, v148, v103, s[58:59]
	v_cndmask_b32_e64 v104, v148, v104, s[60:61]
	v_cndmask_b32_e64 v105, v148, v105, s[62:63]
	v_subrev_u32_e32 v117, 32, v115
	v_cmp_gt_u32_e64 s[48:49], s26, v117
	v_subrev_u32_e32 v117, 33, v115
	v_cmp_gt_u32_e64 s[50:51], s26, v117
	v_subrev_u32_e32 v117, 34, v115
	v_cmp_gt_u32_e64 s[52:53], s26, v117
	v_subrev_u32_e32 v117, 35, v115
	v_cmp_gt_u32_e64 s[54:55], s26, v117
	v_subrev_u32_e32 v117, 48, v115
	v_cmp_gt_u32_e64 s[56:57], s26, v117
	v_subrev_u32_e32 v117, 49, v115
	v_cmp_gt_u32_e64 s[58:59], s26, v117
	v_subrev_u32_e32 v117, 50, v115
	v_cmp_gt_u32_e64 s[60:61], s26, v117
	v_subrev_u32_e32 v117, 51, v115
	v_cmp_gt_u32_e64 s[62:63], s26, v117
	v_cndmask_b32_e64 v106, v148, v106, s[48:49]
	v_cndmask_b32_e64 v107, v148, v107, s[50:51]
	v_cndmask_b32_e64 v108, v148, v108, s[52:53]
	v_cndmask_b32_e64 v109, v148, v109, s[54:55]
	v_cndmask_b32_e64 v110, v148, v110, s[56:57]
	v_cndmask_b32_e64 v111, v148, v111, s[58:59]
	v_cndmask_b32_e64 v112, v148, v112, s[60:61]
	v_cndmask_b32_e64 v113, v148, v113, s[62:63]
	v_max3_f32 v116, v98, v99, v100
	v_max3_f32 v116, v116, v101, v102
	v_max3_f32 v116, v116, v103, v104
	v_max3_f32 v116, v116, v105, v106
	v_max3_f32 v116, v116, v107, v108
	v_max3_f32 v116, v116, v109, v110
	v_max3_f32 v116, v116, v111, v112
	v_max3_f32 v116, v116, v113, s29
	v_mov_b32_e32 v117, v116
	s_nop 1
	v_permlane16_swap_b32_e32 v116, v117
	v_max_f32_e32 v116, v116, v117
	v_mov_b32_e32 v117, v116
	s_nop 1
	v_permlane32_swap_b32_e32 v116, v117
	v_max_f32_e32 v116, v116, v117
	v_max_f32_e32 v121, v167, v116
	v_sub_f32_e32 v118, v167, v121
	v_cmp_lt_f32_e32 vcc, s30, v121
	v_exp_f32_e32 v118, v118
	v_mov_b32_e32 v167, v121
	v_cndmask_b32_e32 v120, 0, v121, vcc
	v_pk_mul_f32 v[30:31], v[30:31], v[118:119] op_sel_hi:[1,0]
	v_pk_mul_f32 v[32:33], v[32:33], v[118:119] op_sel_hi:[1,0]
	v_pk_mul_f32 v[26:27], v[26:27], v[118:119] op_sel_hi:[1,0]
	v_pk_mul_f32 v[28:29], v[28:29], v[118:119] op_sel_hi:[1,0]
	v_pk_mul_f32 v[22:23], v[22:23], v[118:119] op_sel_hi:[1,0]
	v_pk_mul_f32 v[24:25], v[24:25], v[118:119] op_sel_hi:[1,0]
	v_pk_mul_f32 v[18:19], v[18:19], v[118:119] op_sel_hi:[1,0]
	v_pk_mul_f32 v[20:21], v[20:21], v[118:119] op_sel_hi:[1,0]
	v_pk_add_f32 v[98:99], v[98:99], v[120:121] op_sel_hi:[1,0] neg_lo:[0,1] neg_hi:[0,1]
	v_pk_add_f32 v[100:101], v[100:101], v[120:121] op_sel_hi:[1,0] neg_lo:[0,1] neg_hi:[0,1]
	v_pk_add_f32 v[102:103], v[102:103], v[120:121] op_sel_hi:[1,0] neg_lo:[0,1] neg_hi:[0,1]
	v_pk_add_f32 v[104:105], v[104:105], v[120:121] op_sel_hi:[1,0] neg_lo:[0,1] neg_hi:[0,1]
	v_pk_add_f32 v[106:107], v[106:107], v[120:121] op_sel_hi:[1,0] neg_lo:[0,1] neg_hi:[0,1]
	v_pk_add_f32 v[108:109], v[108:109], v[120:121] op_sel_hi:[1,0] neg_lo:[0,1] neg_hi:[0,1]
	v_pk_add_f32 v[110:111], v[110:111], v[120:121] op_sel_hi:[1,0] neg_lo:[0,1] neg_hi:[0,1]
	v_pk_add_f32 v[112:113], v[112:113], v[120:121] op_sel_hi:[1,0] neg_lo:[0,1] neg_hi:[0,1]
	v_exp_f32_e32 v98, v98
	v_exp_f32_e32 v99, v99
	v_exp_f32_e32 v100, v100
	v_exp_f32_e32 v101, v101
	v_exp_f32_e32 v102, v102
	v_exp_f32_e32 v103, v103
	v_exp_f32_e32 v104, v104
	v_exp_f32_e32 v105, v105
	v_exp_f32_e32 v106, v106
	v_exp_f32_e32 v107, v107
	v_exp_f32_e32 v108, v108
	v_exp_f32_e32 v109, v109
	v_exp_f32_e32 v110, v110
	v_exp_f32_e32 v111, v111
	v_exp_f32_e32 v112, v112
	v_exp_f32_e32 v113, v113
	s_nop 0
	v_pk_add_f32 v[82:83], v[98:99], v[100:101]
	v_pk_add_f32 v[84:85], v[102:103], v[104:105]
	v_pk_add_f32 v[86:87], v[106:107], v[108:109]
	v_pk_add_f32 v[88:89], v[110:111], v[112:113]
	v_pk_add_f32 v[82:83], v[82:83], v[84:85]
	v_pk_add_f32 v[86:87], v[86:87], v[88:89]
	s_nop 0
	v_pk_add_f32 v[82:83], v[82:83], v[86:87]
	s_nop 0
	v_add_f32_e32 v82, v82, v83
	v_fma_f32 v159, v159, v118, v82
	v_cvt_pk_bf16_f32 v105, v104, v105
	v_cvt_pk_bf16_f32 v104, v102, v103
	v_cvt_pk_bf16_f32 v103, v100, v101
	v_cvt_pk_bf16_f32 v102, v98, v99
	v_cvt_pk_bf16_f32 v106, v106, v107
	v_cvt_pk_bf16_f32 v107, v108, v109
	v_cvt_pk_bf16_f32 v108, v110, v111
	v_cvt_pk_bf16_f32 v109, v112, v113
	s_branch .Lsw_pv
.Lsw_p1:
	v_lshl_add_u32 v114, s82, 2, v145
	ds_read2_b32 v[82:83], v114 offset0:127 offset1:128
	ds_read2_b32 v[84:85], v114 offset0:129 offset1:130
	ds_read2_b32 v[86:87], v114 offset0:143 offset1:144
	ds_read2_b32 v[88:89], v114 offset0:145 offset1:146
	s_waitcnt lgkmcnt(4)
	v_mfma_f32_16x16x32_bf16 v[70:73], v[70:73], v[2:5], 0
	v_mfma_f32_16x16x32_bf16 v[74:77], v[74:77], v[2:5], 0
	v_mfma_f32_16x16x32_bf16 v[62:65], v[62:65], v[2:5], 0
	v_mfma_f32_16x16x32_bf16 v[54:57], v[54:57], v[2:5], 0
	ds_read2_b32 v[90:91], v114 offset0:159 offset1:160
	ds_read2_b32 v[92:93], v114 offset0:161 offset1:162
	ds_read2_b32 v[94:95], v114 offset0:175 offset1:176
	ds_read2_b32 v[96:97], v114 offset0:177 offset1:178
	v_mfma_f32_16x16x32_bf16 v[70:73], v[78:81], v[6:9], v[70:73]
	v_mfma_f32_16x16x32_bf16 v[74:77], v[66:69], v[6:9], v[74:77]
	v_mfma_f32_16x16x32_bf16 v[62:65], v[58:61], v[6:9], v[62:65]
	v_mfma_f32_16x16x32_bf16 v[54:57], v[50:53], v[6:9], v[54:57]
	s_waitcnt lgkmcnt(0)
	ds_read_b128 v[98:101], v232 offset:32768
	ds_read_b128 v[78:81], v165 offset:32768
	ds_read_b128 v[102:105], v232 offset:34816
	ds_read_b128 v[66:69], v165 offset:34816
	ds_read_b128 v[106:109], v232 offset:36864
	ds_read_b128 v[58:61], v165 offset:36864
	ds_read_b128 v[110:113], v232 offset:38912
	ds_read_b128 v[50:53], v165 offset:38912
	v_pk_fma_f32 v[70:71], v[70:71], s[36:37], v[82:83] op_sel_hi:[1,0,1]
	v_pk_fma_f32 v[72:73], v[72:73], s[36:37], v[84:85] op_sel_hi:[1,0,1]
	v_pk_fma_f32 v[74:75], v[74:75], s[36:37], v[86:87] op_sel_hi:[1,0,1]
	v_pk_fma_f32 v[76:77], v[76:77], s[36:37], v[88:89] op_sel_hi:[1,0,1]
	v_pk_fma_f32 v[62:63], v[62:63], s[36:37], v[90:91] op_sel_hi:[1,0,1]
	v_pk_fma_f32 v[64:65], v[64:65], s[36:37], v[92:93] op_sel_hi:[1,0,1]
	v_pk_fma_f32 v[54:55], v[54:55], s[36:37], v[94:95] op_sel_hi:[1,0,1]
	v_pk_fma_f32 v[56:57], v[56:57], s[36:37], v[96:97] op_sel_hi:[1,0,1]
	v_max3_f32 v116, v70, v71, v72
	v_max3_f32 v116, v116, v73, v74
	v_max3_f32 v116, v116, v75, v76
	v_max3_f32 v116, v116, v77, v62
	v_max3_f32 v116, v116, v63, v64
	v_max3_f32 v116, v116, v65, v54
	v_max3_f32 v116, v116, v55, v56
	v_max3_f32 v116, v116, v57, s29
	v_mov_b32_e32 v117, v116
	s_nop 1
	v_permlane16_swap_b32_e32 v116, v117
	v_max_f32_e32 v116, v116, v117
	v_mov_b32_e32 v117, v116
	s_nop 1
	v_permlane32_swap_b32_e32 v116, v117
	v_max_f32_e32 v116, v116, v117
	v_max_f32_e32 v121, v166, v116
	v_sub_f32_e32 v118, v166, v121
	v_exp_f32_e32 v118, v118
	v_mov_b32_e32 v166, v121
	v_mov_b32_e32 v120, v121
	v_pk_mul_f32 v[46:47], v[46:47], v[118:119] op_sel_hi:[1,0]
	v_pk_mul_f32 v[48:49], v[48:49], v[118:119] op_sel_hi:[1,0]
	v_pk_mul_f32 v[42:43], v[42:43], v[118:119] op_sel_hi:[1,0]
	v_pk_mul_f32 v[44:45], v[44:45], v[118:119] op_sel_hi:[1,0]
	v_pk_mul_f32 v[38:39], v[38:39], v[118:119] op_sel_hi:[1,0]
	v_pk_mul_f32 v[40:41], v[40:41], v[118:119] op_sel_hi:[1,0]
	v_pk_mul_f32 v[34:35], v[34:35], v[118:119] op_sel_hi:[1,0]
	v_pk_mul_f32 v[36:37], v[36:37], v[118:119] op_sel_hi:[1,0]
	v_pk_add_f32 v[70:71], v[70:71], v[120:121] op_sel_hi:[1,0] neg_lo:[0,1] neg_hi:[0,1]
	v_pk_add_f32 v[72:73], v[72:73], v[120:121] op_sel_hi:[1,0] neg_lo:[0,1] neg_hi:[0,1]
	v_pk_add_f32 v[74:75], v[74:75], v[120:121] op_sel_hi:[1,0] neg_lo:[0,1] neg_hi:[0,1]
	v_pk_add_f32 v[76:77], v[76:77], v[120:121] op_sel_hi:[1,0] neg_lo:[0,1] neg_hi:[0,1]
	v_pk_add_f32 v[62:63], v[62:63], v[120:121] op_sel_hi:[1,0] neg_lo:[0,1] neg_hi:[0,1]
	v_pk_add_f32 v[64:65], v[64:65], v[120:121] op_sel_hi:[1,0] neg_lo:[0,1] neg_hi:[0,1]
	v_pk_add_f32 v[54:55], v[54:55], v[120:121] op_sel_hi:[1,0] neg_lo:[0,1] neg_hi:[0,1]
	v_pk_add_f32 v[56:57], v[56:57], v[120:121] op_sel_hi:[1,0] neg_lo:[0,1] neg_hi:[0,1]
	v_exp_f32_e32 v70, v70
	v_exp_f32_e32 v71, v71
	v_exp_f32_e32 v72, v72
	v_exp_f32_e32 v73, v73
	v_exp_f32_e32 v74, v74
	v_exp_f32_e32 v75, v75
	v_exp_f32_e32 v76, v76
	v_exp_f32_e32 v77, v77
	v_exp_f32_e32 v62, v62
	v_exp_f32_e32 v63, v63
	v_exp_f32_e32 v64, v64
	v_exp_f32_e32 v65, v65
	v_exp_f32_e32 v54, v54
	v_exp_f32_e32 v55, v55
	v_exp_f32_e32 v56, v56
	v_exp_f32_e32 v57, v57
	s_nop 0
	v_pk_add_f32 v[82:83], v[70:71], v[72:73]
	v_pk_add_f32 v[84:85], v[74:75], v[76:77]
	v_pk_add_f32 v[86:87], v[62:63], v[64:65]
	v_pk_add_f32 v[88:89], v[54:55], v[56:57]
	v_pk_add_f32 v[82:83], v[82:83], v[84:85]
	v_pk_add_f32 v[86:87], v[86:87], v[88:89]
	s_nop 0
	v_pk_add_f32 v[82:83], v[82:83], v[86:87]
	s_nop 0
	v_add_f32_e32 v82, v82, v83
	v_fma_f32 v158, v158, v118, v82
	v_cvt_pk_bf16_f32 v77, v76, v77
	v_cvt_pk_bf16_f32 v76, v74, v75
	v_cvt_pk_bf16_f32 v75, v72, v73
	v_cvt_pk_bf16_f32 v74, v70, v71
	v_cvt_pk_bf16_f32 v62, v62, v63
	v_cvt_pk_bf16_f32 v63, v64, v65
	v_cvt_pk_bf16_f32 v64, v54, v55
	v_cvt_pk_bf16_f32 v65, v56, v57
	s_waitcnt lgkmcnt(0)
	ds_read2_b32 v[82:83], v114 offset0:111 offset1:112
	ds_read2_b32 v[84:85], v114 offset0:113 offset1:114
	ds_read2_b32 v[86:87], v114 offset0:127 offset1:128
	ds_read2_b32 v[88:89], v114 offset0:129 offset1:130
	ds_read2_b32 v[90:91], v114 offset0:143 offset1:144
	ds_read2_b32 v[92:93], v114 offset0:145 offset1:146
	ds_read2_b32 v[94:95], v114 offset0:159 offset1:160
	ds_read2_b32 v[96:97], v114 offset0:161 offset1:162
	v_mfma_f32_16x16x32_bf16 v[98:101], v[98:101], v[10:13], 0
	v_mfma_f32_16x16x32_bf16 v[102:105], v[102:105], v[10:13], 0
	v_mfma_f32_16x16x32_bf16 v[106:109], v[106:109], v[10:13], 0
	v_mfma_f32_16x16x32_bf16 v[110:113], v[110:113], v[10:13], 0
	v_mfma_f32_16x16x32_bf16 v[98:101], v[78:81], v[14:17], v[98:101]
	v_mfma_f32_16x16x32_bf16 v[102:105], v[66:69], v[14:17], v[102:105]
	v_mfma_f32_16x16x32_bf16 v[106:109], v[58:61], v[14:17], v[106:109]
	v_mfma_f32_16x16x32_bf16 v[110:113], v[50:53], v[14:17], v[110:113]
	s_waitcnt lgkmcnt(0)
	s_nop 6
	v_pk_fma_f32 v[98:99], v[98:99], s[36:37], v[82:83] op_sel_hi:[1,0,1]
	v_pk_fma_f32 v[100:101], v[100:101], s[36:37], v[84:85] op_sel_hi:[1,0,1]
	v_pk_fma_f32 v[102:103], v[102:103], s[36:37], v[86:87] op_sel_hi:[1,0,1]
	v_pk_fma_f32 v[104:105], v[104:105], s[36:37], v[88:89] op_sel_hi:[1,0,1]
	v_pk_fma_f32 v[106:107], v[106:107], s[36:37], v[90:91] op_sel_hi:[1,0,1]
	v_pk_fma_f32 v[108:109], v[108:109], s[36:37], v[92:93] op_sel_hi:[1,0,1]
	v_pk_fma_f32 v[110:111], v[110:111], s[36:37], v[94:95] op_sel_hi:[1,0,1]
	v_pk_fma_f32 v[112:113], v[112:113], s[36:37], v[96:97] op_sel_hi:[1,0,1]
	v_max3_f32 v116, v98, v99, v100
	v_max3_f32 v116, v116, v101, v102
	v_max3_f32 v116, v116, v103, v104
	v_max3_f32 v116, v116, v105, v106
	v_max3_f32 v116, v116, v107, v108
	v_max3_f32 v116, v116, v109, v110
	v_max3_f32 v116, v116, v111, v112
	v_max3_f32 v116, v116, v113, s29
	v_mov_b32_e32 v117, v116
	s_nop 1
	v_permlane16_swap_b32_e32 v116, v117
	v_max_f32_e32 v116, v116, v117
	v_mov_b32_e32 v117, v116
	s_nop 1
	v_permlane32_swap_b32_e32 v116, v117
	v_max_f32_e32 v116, v116, v117
	v_max_f32_e32 v121, v167, v116
	v_sub_f32_e32 v118, v167, v121
	v_exp_f32_e32 v118, v118
	v_mov_b32_e32 v167, v121
	v_mov_b32_e32 v120, v121
	v_pk_mul_f32 v[30:31], v[30:31], v[118:119] op_sel_hi:[1,0]
	v_pk_mul_f32 v[32:33], v[32:33], v[118:119] op_sel_hi:[1,0]
	v_pk_mul_f32 v[26:27], v[26:27], v[118:119] op_sel_hi:[1,0]
	v_pk_mul_f32 v[28:29], v[28:29], v[118:119] op_sel_hi:[1,0]
	v_pk_mul_f32 v[22:23], v[22:23], v[118:119] op_sel_hi:[1,0]
	v_pk_mul_f32 v[24:25], v[24:25], v[118:119] op_sel_hi:[1,0]
	v_pk_mul_f32 v[18:19], v[18:19], v[118:119] op_sel_hi:[1,0]
	v_pk_mul_f32 v[20:21], v[20:21], v[118:119] op_sel_hi:[1,0]
	v_pk_add_f32 v[98:99], v[98:99], v[120:121] op_sel_hi:[1,0] neg_lo:[0,1] neg_hi:[0,1]
	v_pk_add_f32 v[100:101], v[100:101], v[120:121] op_sel_hi:[1,0] neg_lo:[0,1] neg_hi:[0,1]
	v_pk_add_f32 v[102:103], v[102:103], v[120:121] op_sel_hi:[1,0] neg_lo:[0,1] neg_hi:[0,1]
	v_pk_add_f32 v[104:105], v[104:105], v[120:121] op_sel_hi:[1,0] neg_lo:[0,1] neg_hi:[0,1]
	v_pk_add_f32 v[106:107], v[106:107], v[120:121] op_sel_hi:[1,0] neg_lo:[0,1] neg_hi:[0,1]
	v_pk_add_f32 v[108:109], v[108:109], v[120:121] op_sel_hi:[1,0] neg_lo:[0,1] neg_hi:[0,1]
	v_pk_add_f32 v[110:111], v[110:111], v[120:121] op_sel_hi:[1,0] neg_lo:[0,1] neg_hi:[0,1]
	v_pk_add_f32 v[112:113], v[112:113], v[120:121] op_sel_hi:[1,0] neg_lo:[0,1] neg_hi:[0,1]
	v_exp_f32_e32 v98, v98
	v_exp_f32_e32 v99, v99
	v_exp_f32_e32 v100, v100
	v_exp_f32_e32 v101, v101
	v_exp_f32_e32 v102, v102
	v_exp_f32_e32 v103, v103
	v_exp_f32_e32 v104, v104
	v_exp_f32_e32 v105, v105
	v_exp_f32_e32 v106, v106
	v_exp_f32_e32 v107, v107
	v_exp_f32_e32 v108, v108
	v_exp_f32_e32 v109, v109
	v_exp_f32_e32 v110, v110
	v_exp_f32_e32 v111, v111
	v_exp_f32_e32 v112, v112
	v_exp_f32_e32 v113, v113
	s_nop 0
	v_pk_add_f32 v[82:83], v[98:99], v[100:101]
	v_pk_add_f32 v[84:85], v[102:103], v[104:105]
	v_pk_add_f32 v[86:87], v[106:107], v[108:109]
	v_pk_add_f32 v[88:89], v[110:111], v[112:113]
	v_pk_add_f32 v[82:83], v[82:83], v[84:85]
	v_pk_add_f32 v[86:87], v[86:87], v[88:89]
	s_nop 0
	v_pk_add_f32 v[82:83], v[82:83], v[86:87]
	s_nop 0
	v_add_f32_e32 v82, v82, v83
	v_fma_f32 v159, v159, v118, v82
	v_cvt_pk_bf16_f32 v105, v104, v105
	v_cvt_pk_bf16_f32 v104, v102, v103
	v_cvt_pk_bf16_f32 v103, v100, v101
	v_cvt_pk_bf16_f32 v102, v98, v99
	v_cvt_pk_bf16_f32 v106, v106, v107
	v_cvt_pk_bf16_f32 v107, v108, v109
	v_cvt_pk_bf16_f32 v108, v110, v111
	v_cvt_pk_bf16_f32 v109, v112, v113

.LBB0_287:
	s_or_b32 s16, s25, s19
	s_cmp_gt_i32 s16, s14
	s_cbranch_scc1 .LBB0_286
	s_lshl_b32 s16, s16, 14
	s_and_b32 s16, s16, 0xc000
	s_add_i32 s16, s16, 0
	s_waitcnt lgkmcnt(0)
	v_add_u32_e32 v50, s16, v215
	v_and_b32_e32 v51, 64, v147
	v_add_u32_e32 v232, v50, v213
	v_add_u32_e32 v82, 64, v51
	v_add_u32_e32 v159, v50, v214
	ds_read_b128 v[78:81], v232 offset:32768
	ds_read_b128 v[70:73], v232 offset:34816
	ds_read_b128 v[74:77], v159 offset:32768
	ds_read_b128 v[66:69], v159 offset:34816
	ds_read_b128 v[62:65], v232 offset:36864
	ds_read_b128 v[54:57], v232 offset:38912
	ds_read_b128 v[58:61], v159 offset:36864
	ds_read_b128 v[50:53], v159 offset:38912
	s_add_i32 s25, s25, s23
	s_lshl_b32 s25, s25, 6
	s_or_b32 s42, s25, 63
	s_cmp_le_i32 s42, s4
	s_cselect_b64 s[42:43], -1, 0
	s_sub_i32 s44, s18, s25
	v_xor_b32_e32 v0, 16, v147
	s_cmpk_lt_i32 s44, 0x200
	v_cmp_lt_i32_e32 vcc, v0, v82
	v_xor_b32_e32 v83, 32, v147
	s_cselect_b64 s[44:45], -1, 0
	v_cndmask_b32_e32 v0, v147, v0, vcc
	v_cmp_lt_i32_e32 vcc, v83, v82
	s_and_b64 s[42:43], s[42:43], s[44:45]
	v_lshlrev_b32_e32 v0, 2, v0
	v_cndmask_b32_e32 v82, v147, v83, vcc
	v_lshlrev_b32_e32 v149, 2, v82
	s_andn2_b64 vcc, exec, s[42:43]
	s_mov_b64 s[42:43], -1
	s_cbranch_vccz .Lnw_p1
	v_lshl_add_u32 v114, s25, 2, v145
	v_add_u32_e32 v115, 0xffc, v114
	ds_read2_b32 v[82:83], v115 offset1:1
	ds_read2_b32 v[84:85], v115 offset0:2 offset1:3
	ds_read2_b32 v[86:87], v115 offset0:16 offset1:17
	ds_read2_b32 v[88:89], v115 offset0:18 offset1:19
	s_waitcnt lgkmcnt(4)
	v_mfma_f32_16x16x32_bf16 v[78:81], v[78:81], v[2:5], 0
	v_mfma_f32_16x16x32_bf16 v[70:73], v[70:73], v[2:5], 0
	v_mfma_f32_16x16x32_bf16 v[62:65], v[62:65], v[2:5], 0
	v_mfma_f32_16x16x32_bf16 v[54:57], v[54:57], v[2:5], 0
	ds_read2_b32 v[90:91], v115 offset0:32 offset1:33
	ds_read2_b32 v[92:93], v115 offset0:34 offset1:35
	ds_read2_b32 v[94:95], v115 offset0:48 offset1:49
	ds_read2_b32 v[96:97], v115 offset0:50 offset1:51
	v_mfma_f32_16x16x32_bf16 v[78:81], v[74:77], v[6:9], v[78:81]
	v_mfma_f32_16x16x32_bf16 v[70:73], v[66:69], v[6:9], v[70:73]
	v_mfma_f32_16x16x32_bf16 v[62:65], v[58:61], v[6:9], v[62:65]
	v_mfma_f32_16x16x32_bf16 v[54:57], v[50:53], v[6:9], v[54:57]
	s_waitcnt lgkmcnt(0)
	ds_read_b128 v[98:101], v232 offset:32768
	ds_read_b128 v[74:77], v159 offset:32768
	ds_read_b128 v[102:105], v232 offset:34816
	ds_read_b128 v[66:69], v159 offset:34816
	ds_read_b128 v[106:109], v232 offset:36864
	ds_read_b128 v[58:61], v159 offset:36864
	ds_read_b128 v[110:113], v232 offset:38912
	ds_read_b128 v[50:53], v159 offset:38912
	v_pk_fma_f32 v[78:79], v[78:79], s[36:37], v[82:83] op_sel_hi:[1,0,1]
	v_pk_fma_f32 v[80:81], v[80:81], s[36:37], v[84:85] op_sel_hi:[1,0,1]
	v_pk_fma_f32 v[70:71], v[70:71], s[36:37], v[86:87] op_sel_hi:[1,0,1]
	v_pk_fma_f32 v[72:73], v[72:73], s[36:37], v[88:89] op_sel_hi:[1,0,1]
	v_pk_fma_f32 v[62:63], v[62:63], s[36:37], v[90:91] op_sel_hi:[1,0,1]
	v_pk_fma_f32 v[64:65], v[64:65], s[36:37], v[92:93] op_sel_hi:[1,0,1]
	v_pk_fma_f32 v[54:55], v[54:55], s[36:37], v[94:95] op_sel_hi:[1,0,1]
	v_pk_fma_f32 v[56:57], v[56:57], s[36:37], v[96:97] op_sel_hi:[1,0,1]
	v_or_b32_e32 v117, s25, v216
	v_sub_u32_e32 v115, v144, v117
	v_subrev_u32_e32 v117, 0, v115
	v_cmp_gt_u32_e64 s[48:49], s3, v117
	v_subrev_u32_e32 v117, 1, v115
	v_cmp_gt_u32_e64 s[50:51], s3, v117
	v_subrev_u32_e32 v117, 2, v115
	v_cmp_gt_u32_e64 s[52:53], s3, v117
	v_subrev_u32_e32 v117, 3, v115
	v_cmp_gt_u32_e64 s[54:55], s3, v117
	v_subrev_u32_e32 v117, 16, v115
	v_cmp_gt_u32_e64 s[56:57], s3, v117
	v_subrev_u32_e32 v117, 17, v115
	v_cmp_gt_u32_e64 s[58:59], s3, v117
	v_subrev_u32_e32 v117, 18, v115
	v_cmp_gt_u32_e64 s[60:61], s3, v117
	v_subrev_u32_e32 v117, 19, v115
	v_cmp_gt_u32_e64 s[62:63], s3, v117
	v_cndmask_b32_e64 v78, v148, v78, s[48:49]
	v_cndmask_b32_e64 v79, v148, v79, s[50:51]
	v_cndmask_b32_e64 v80, v148, v80, s[52:53]
	v_cndmask_b32_e64 v81, v148, v81, s[54:55]
	v_cndmask_b32_e64 v70, v148, v70, s[56:57]
	v_cndmask_b32_e64 v71, v148, v71, s[58:59]
	v_cndmask_b32_e64 v72, v148, v72, s[60:61]
	v_cndmask_b32_e64 v73, v148, v73, s[62:63]
	v_subrev_u32_e32 v117, 32, v115
	v_cmp_gt_u32_e64 s[48:49], s3, v117
	v_subrev_u32_e32 v117, 33, v115
	v_cmp_gt_u32_e64 s[50:51], s3, v117
	v_subrev_u32_e32 v117, 34, v115
	v_cmp_gt_u32_e64 s[52:53], s3, v117
	v_subrev_u32_e32 v117, 35, v115
	v_cmp_gt_u32_e64 s[54:55], s3, v117
	v_subrev_u32_e32 v117, 48, v115
	v_cmp_gt_u32_e64 s[56:57], s3, v117
	v_subrev_u32_e32 v117, 49, v115
	v_cmp_gt_u32_e64 s[58:59], s3, v117
	v_subrev_u32_e32 v117, 50, v115
	v_cmp_gt_u32_e64 s[60:61], s3, v117
	v_subrev_u32_e32 v117, 51, v115
	v_cmp_gt_u32_e64 s[62:63], s3, v117
	v_cndmask_b32_e64 v62, v148, v62, s[48:49]
	v_cndmask_b32_e64 v63, v148, v63, s[50:51]
	v_cndmask_b32_e64 v64, v148, v64, s[52:53]
	v_cndmask_b32_e64 v65, v148, v65, s[54:55]
	v_cndmask_b32_e64 v54, v148, v54, s[56:57]
	v_cndmask_b32_e64 v55, v148, v55, s[58:59]
	v_cndmask_b32_e64 v56, v148, v56, s[60:61]
	v_cndmask_b32_e64 v57, v148, v57, s[62:63]
	v_max3_f32 v116, v78, v79, v80
	v_max3_f32 v116, v116, v81, v70
	v_max3_f32 v116, v116, v71, v72
	v_max3_f32 v116, v116, v73, v62
	v_max3_f32 v116, v116, v63, v64
	v_max3_f32 v116, v116, v65, v54
	v_max3_f32 v116, v116, v55, v56
	v_max3_f32 v116, v116, v57, s29
	v_mov_b32_e32 v117, v116
	s_nop 1
	v_permlane16_swap_b32_e32 v116, v117
	v_max_f32_e32 v116, v116, v117
	v_mov_b32_e32 v117, v116
	s_nop 1
	v_permlane32_swap_b32_e32 v116, v117
	v_max_f32_e32 v116, v116, v117
	v_max_f32_e32 v121, v166, v116
	v_sub_f32_e32 v118, v166, v121
	v_cmp_lt_f32_e32 vcc, s30, v121
	v_exp_f32_e32 v118, v118
	v_mov_b32_e32 v166, v121
	v_cndmask_b32_e32 v120, 0, v121, vcc
	v_pk_mul_f32 v[46:47], v[46:47], v[118:119] op_sel_hi:[1,0]
	v_pk_mul_f32 v[48:49], v[48:49], v[118:119] op_sel_hi:[1,0]
	v_pk_mul_f32 v[42:43], v[42:43], v[118:119] op_sel_hi:[1,0]
	v_pk_mul_f32 v[44:45], v[44:45], v[118:119] op_sel_hi:[1,0]
	v_pk_mul_f32 v[38:39], v[38:39], v[118:119] op_sel_hi:[1,0]
	v_pk_mul_f32 v[40:41], v[40:41], v[118:119] op_sel_hi:[1,0]
	v_pk_mul_f32 v[34:35], v[34:35], v[118:119] op_sel_hi:[1,0]
	v_pk_mul_f32 v[36:37], v[36:37], v[118:119] op_sel_hi:[1,0]
	v_pk_add_f32 v[78:79], v[78:79], v[120:121] op_sel_hi:[1,0] neg_lo:[0,1] neg_hi:[0,1]
	v_pk_add_f32 v[80:81], v[80:81], v[120:121] op_sel_hi:[1,0] neg_lo:[0,1] neg_hi:[0,1]
	v_pk_add_f32 v[70:71], v[70:71], v[120:121] op_sel_hi:[1,0] neg_lo:[0,1] neg_hi:[0,1]
	v_pk_add_f32 v[72:73], v[72:73], v[120:121] op_sel_hi:[1,0] neg_lo:[0,1] neg_hi:[0,1]
	v_pk_add_f32 v[62:63], v[62:63], v[120:121] op_sel_hi:[1,0] neg_lo:[0,1] neg_hi:[0,1]
	v_pk_add_f32 v[64:65], v[64:65], v[120:121] op_sel_hi:[1,0] neg_lo:[0,1] neg_hi:[0,1]
	v_pk_add_f32 v[54:55], v[54:55], v[120:121] op_sel_hi:[1,0] neg_lo:[0,1] neg_hi:[0,1]
	v_pk_add_f32 v[56:57], v[56:57], v[120:121] op_sel_hi:[1,0] neg_lo:[0,1] neg_hi:[0,1]
	v_exp_f32_e32 v78, v78
	v_exp_f32_e32 v79, v79
	v_exp_f32_e32 v80, v80
	v_exp_f32_e32 v81, v81
	v_exp_f32_e32 v70, v70
	v_exp_f32_e32 v71, v71
	v_exp_f32_e32 v72, v72
	v_exp_f32_e32 v73, v73
	v_exp_f32_e32 v62, v62
	v_exp_f32_e32 v63, v63
	v_exp_f32_e32 v64, v64
	v_exp_f32_e32 v65, v65
	v_exp_f32_e32 v54, v54
	v_exp_f32_e32 v55, v55
	v_exp_f32_e32 v56, v56
	v_exp_f32_e32 v57, v57
	s_nop 0
	v_pk_add_f32 v[82:83], v[78:79], v[80:81]
	v_pk_add_f32 v[84:85], v[70:71], v[72:73]
	v_pk_add_f32 v[86:87], v[62:63], v[64:65]
	v_pk_add_f32 v[88:89], v[54:55], v[56:57]
	v_pk_add_f32 v[82:83], v[82:83], v[84:85]
	v_pk_add_f32 v[86:87], v[86:87], v[88:89]
	s_nop 0
	v_pk_add_f32 v[82:83], v[82:83], v[86:87]
	s_nop 0
	v_add_f32_e32 v82, v82, v83
	v_fma_f32 v160, v160, v118, v82
	v_cvt_pk_bf16_f32 v73, v72, v73
	v_cvt_pk_bf16_f32 v72, v70, v71
	v_cvt_pk_bf16_f32 v71, v80, v81
	v_cvt_pk_bf16_f32 v70, v78, v79
	v_cvt_pk_bf16_f32 v62, v62, v63
	v_cvt_pk_bf16_f32 v63, v64, v65
	v_cvt_pk_bf16_f32 v64, v54, v55
	v_cvt_pk_bf16_f32 v65, v56, v57
	v_add_u32_e32 v115, 0xfbc, v114
	s_waitcnt lgkmcnt(0)
	ds_read2_b32 v[82:83], v115 offset1:1
	ds_read2_b32 v[84:85], v115 offset0:2 offset1:3
	ds_read2_b32 v[86:87], v115 offset0:16 offset1:17
	ds_read2_b32 v[88:89], v115 offset0:18 offset1:19
	ds_read2_b32 v[90:91], v115 offset0:32 offset1:33
	ds_read2_b32 v[92:93], v115 offset0:34 offset1:35
	ds_read2_b32 v[94:95], v115 offset0:48 offset1:49
	ds_read2_b32 v[96:97], v115 offset0:50 offset1:51
	v_mfma_f32_16x16x32_bf16 v[98:101], v[98:101], v[10:13], 0
	v_mfma_f32_16x16x32_bf16 v[102:105], v[102:105], v[10:13], 0
	v_mfma_f32_16x16x32_bf16 v[106:109], v[106:109], v[10:13], 0
	v_mfma_f32_16x16x32_bf16 v[110:113], v[110:113], v[10:13], 0
	v_mfma_f32_16x16x32_bf16 v[98:101], v[74:77], v[14:17], v[98:101]
	v_mfma_f32_16x16x32_bf16 v[102:105], v[66:69], v[14:17], v[102:105]
	v_mfma_f32_16x16x32_bf16 v[106:109], v[58:61], v[14:17], v[106:109]
	v_mfma_f32_16x16x32_bf16 v[110:113], v[50:53], v[14:17], v[110:113]
	s_waitcnt lgkmcnt(0)
	s_nop 6
	v_pk_fma_f32 v[98:99], v[98:99], s[36:37], v[82:83] op_sel_hi:[1,0,1]
	v_pk_fma_f32 v[100:101], v[100:101], s[36:37], v[84:85] op_sel_hi:[1,0,1]
	v_pk_fma_f32 v[102:103], v[102:103], s[36:37], v[86:87] op_sel_hi:[1,0,1]
	v_pk_fma_f32 v[104:105], v[104:105], s[36:37], v[88:89] op_sel_hi:[1,0,1]
	v_pk_fma_f32 v[106:107], v[106:107], s[36:37], v[90:91] op_sel_hi:[1,0,1]
	v_pk_fma_f32 v[108:109], v[108:109], s[36:37], v[92:93] op_sel_hi:[1,0,1]
	v_pk_fma_f32 v[110:111], v[110:111], s[36:37], v[94:95] op_sel_hi:[1,0,1]
	v_pk_fma_f32 v[112:113], v[112:113], s[36:37], v[96:97] op_sel_hi:[1,0,1]
	v_or_b32_e32 v117, s25, v216
	v_sub_u32_e32 v115, v144, v117
	v_add_u32_e32 v115, 16, v115
	v_subrev_u32_e32 v117, 0, v115
	v_cmp_gt_u32_e64 s[48:49], s3, v117
	v_subrev_u32_e32 v117, 1, v115
	v_cmp_gt_u32_e64 s[50:51], s3, v117
	v_subrev_u32_e32 v117, 2, v115
	v_cmp_gt_u32_e64 s[52:53], s3, v117
	v_subrev_u32_e32 v117, 3, v115
	v_cmp_gt_u32_e64 s[54:55], s3, v117
	v_subrev_u32_e32 v117, 16, v115
	v_cmp_gt_u32_e64 s[56:57], s3, v117
	v_subrev_u32_e32 v117, 17, v115
	v_cmp_gt_u32_e64 s[58:59], s3, v117
	v_subrev_u32_e32 v117, 18, v115
	v_cmp_gt_u32_e64 s[60:61], s3, v117
	v_subrev_u32_e32 v117, 19, v115
	v_cmp_gt_u32_e64 s[62:63], s3, v117
	v_cndmask_b32_e64 v98, v148, v98, s[48:49]
	v_cndmask_b32_e64 v99, v148, v99, s[50:51]
	v_cndmask_b32_e64 v100, v148, v100, s[52:53]
	v_cndmask_b32_e64 v101, v148, v101, s[54:55]
	v_cndmask_b32_e64 v102, v148, v102, s[56:57]
	v_cndmask_b32_e64 v103, v148, v103, s[58:59]
	v_cndmask_b32_e64 v104, v148, v104, s[60:61]
	v_cndmask_b32_e64 v105, v148, v105, s[62:63]
	v_subrev_u32_e32 v117, 32, v115
	v_cmp_gt_u32_e64 s[48:49], s3, v117
	v_subrev_u32_e32 v117, 33, v115
	v_cmp_gt_u32_e64 s[50:51], s3, v117
	v_subrev_u32_e32 v117, 34, v115
	v_cmp_gt_u32_e64 s[52:53], s3, v117
	v_subrev_u32_e32 v117, 35, v115
	v_cmp_gt_u32_e64 s[54:55], s3, v117
	v_subrev_u32_e32 v117, 48, v115
	v_cmp_gt_u32_e64 s[56:57], s3, v117
	v_subrev_u32_e32 v117, 49, v115
	v_cmp_gt_u32_e64 s[58:59], s3, v117
	v_subrev_u32_e32 v117, 50, v115
	v_cmp_gt_u32_e64 s[60:61], s3, v117
	v_subrev_u32_e32 v117, 51, v115
	v_cmp_gt_u32_e64 s[62:63], s3, v117
	v_cndmask_b32_e64 v106, v148, v106, s[48:49]
	v_cndmask_b32_e64 v107, v148, v107, s[50:51]
	v_cndmask_b32_e64 v108, v148, v108, s[52:53]
	v_cndmask_b32_e64 v109, v148, v109, s[54:55]
	v_cndmask_b32_e64 v110, v148, v110, s[56:57]
	v_cndmask_b32_e64 v111, v148, v111, s[58:59]
	v_cndmask_b32_e64 v112, v148, v112, s[60:61]
	v_cndmask_b32_e64 v113, v148, v113, s[62:63]
	v_max3_f32 v116, v98, v99, v100
	v_max3_f32 v116, v116, v101, v102
	v_max3_f32 v116, v116, v103, v104
	v_max3_f32 v116, v116, v105, v106
	v_max3_f32 v116, v116, v107, v108
	v_max3_f32 v116, v116, v109, v110
	v_max3_f32 v116, v116, v111, v112
	v_max3_f32 v116, v116, v113, s29
	v_mov_b32_e32 v117, v116
	s_nop 1
	v_permlane16_swap_b32_e32 v116, v117
	v_max_f32_e32 v116, v116, v117
	v_mov_b32_e32 v117, v116
	s_nop 1
	v_permlane32_swap_b32_e32 v116, v117
	v_max_f32_e32 v116, v116, v117
	v_max_f32_e32 v121, v167, v116
	v_sub_f32_e32 v118, v167, v121
	v_cmp_lt_f32_e32 vcc, s30, v121
	v_exp_f32_e32 v118, v118
	v_mov_b32_e32 v167, v121
	v_cndmask_b32_e32 v120, 0, v121, vcc
	v_pk_mul_f32 v[30:31], v[30:31], v[118:119] op_sel_hi:[1,0]
	v_pk_mul_f32 v[32:33], v[32:33], v[118:119] op_sel_hi:[1,0]
	v_pk_mul_f32 v[26:27], v[26:27], v[118:119] op_sel_hi:[1,0]
	v_pk_mul_f32 v[28:29], v[28:29], v[118:119] op_sel_hi:[1,0]
	v_pk_mul_f32 v[22:23], v[22:23], v[118:119] op_sel_hi:[1,0]
	v_pk_mul_f32 v[24:25], v[24:25], v[118:119] op_sel_hi:[1,0]
	v_pk_mul_f32 v[18:19], v[18:19], v[118:119] op_sel_hi:[1,0]
	v_pk_mul_f32 v[20:21], v[20:21], v[118:119] op_sel_hi:[1,0]
	v_pk_add_f32 v[98:99], v[98:99], v[120:121] op_sel_hi:[1,0] neg_lo:[0,1] neg_hi:[0,1]
	v_pk_add_f32 v[100:101], v[100:101], v[120:121] op_sel_hi:[1,0] neg_lo:[0,1] neg_hi:[0,1]
	v_pk_add_f32 v[102:103], v[102:103], v[120:121] op_sel_hi:[1,0] neg_lo:[0,1] neg_hi:[0,1]
	v_pk_add_f32 v[104:105], v[104:105], v[120:121] op_sel_hi:[1,0] neg_lo:[0,1] neg_hi:[0,1]
	v_pk_add_f32 v[106:107], v[106:107], v[120:121] op_sel_hi:[1,0] neg_lo:[0,1] neg_hi:[0,1]
	v_pk_add_f32 v[108:109], v[108:109], v[120:121] op_sel_hi:[1,0] neg_lo:[0,1] neg_hi:[0,1]
	v_pk_add_f32 v[110:111], v[110:111], v[120:121] op_sel_hi:[1,0] neg_lo:[0,1] neg_hi:[0,1]
	v_pk_add_f32 v[112:113], v[112:113], v[120:121] op_sel_hi:[1,0] neg_lo:[0,1] neg_hi:[0,1]
	v_exp_f32_e32 v98, v98
	v_exp_f32_e32 v99, v99
	v_exp_f32_e32 v100, v100
	v_exp_f32_e32 v101, v101
	v_exp_f32_e32 v102, v102
	v_exp_f32_e32 v103, v103
	v_exp_f32_e32 v104, v104
	v_exp_f32_e32 v105, v105
	v_exp_f32_e32 v106, v106
	v_exp_f32_e32 v107, v107
	v_exp_f32_e32 v108, v108
	v_exp_f32_e32 v109, v109
	v_exp_f32_e32 v110, v110
	v_exp_f32_e32 v111, v111
	v_exp_f32_e32 v112, v112
	v_exp_f32_e32 v113, v113
	s_nop 0
	v_pk_add_f32 v[82:83], v[98:99], v[100:101]
	v_pk_add_f32 v[84:85], v[102:103], v[104:105]
	v_pk_add_f32 v[86:87], v[106:107], v[108:109]
	v_pk_add_f32 v[88:89], v[110:111], v[112:113]
	v_pk_add_f32 v[82:83], v[82:83], v[84:85]
	v_pk_add_f32 v[86:87], v[86:87], v[88:89]
	s_nop 0
	v_pk_add_f32 v[82:83], v[82:83], v[86:87]
	s_nop 0
	v_add_f32_e32 v82, v82, v83
	v_fma_f32 v161, v161, v118, v82
	v_cvt_pk_bf16_f32 v105, v104, v105
	v_cvt_pk_bf16_f32 v104, v102, v103
	v_cvt_pk_bf16_f32 v103, v100, v101
	v_cvt_pk_bf16_f32 v102, v98, v99
	v_cvt_pk_bf16_f32 v106, v106, v107
	v_cvt_pk_bf16_f32 v107, v108, v109
	v_cvt_pk_bf16_f32 v108, v110, v111
	v_cvt_pk_bf16_f32 v109, v112, v113
	s_branch .Lnw_pv
.Lnw_p1:
	v_lshl_add_u32 v114, s25, 2, v145
	v_add_u32_e32 v115, 0xffc, v114
	ds_read2_b32 v[82:83], v115 offset1:1
	ds_read2_b32 v[84:85], v115 offset0:2 offset1:3
	ds_read2_b32 v[86:87], v115 offset0:16 offset1:17
	ds_read2_b32 v[88:89], v115 offset0:18 offset1:19
	s_waitcnt lgkmcnt(4)
	v_mfma_f32_16x16x32_bf16 v[78:81], v[78:81], v[2:5], 0
	v_mfma_f32_16x16x32_bf16 v[70:73], v[70:73], v[2:5], 0
	v_mfma_f32_16x16x32_bf16 v[62:65], v[62:65], v[2:5], 0
	v_mfma_f32_16x16x32_bf16 v[54:57], v[54:57], v[2:5], 0
	ds_read2_b32 v[90:91], v115 offset0:32 offset1:33
	ds_read2_b32 v[92:93], v115 offset0:34 offset1:35
	ds_read2_b32 v[94:95], v115 offset0:48 offset1:49
	ds_read2_b32 v[96:97], v115 offset0:50 offset1:51
	v_mfma_f32_16x16x32_bf16 v[78:81], v[74:77], v[6:9], v[78:81]
	v_mfma_f32_16x16x32_bf16 v[70:73], v[66:69], v[6:9], v[70:73]
	v_mfma_f32_16x16x32_bf16 v[62:65], v[58:61], v[6:9], v[62:65]
	v_mfma_f32_16x16x32_bf16 v[54:57], v[50:53], v[6:9], v[54:57]
	s_waitcnt lgkmcnt(0)
	ds_read_b128 v[98:101], v232 offset:32768
	ds_read_b128 v[74:77], v159 offset:32768
	ds_read_b128 v[102:105], v232 offset:34816
	ds_read_b128 v[66:69], v159 offset:34816
	ds_read_b128 v[106:109], v232 offset:36864
	ds_read_b128 v[58:61], v159 offset:36864
	ds_read_b128 v[110:113], v232 offset:38912
	ds_read_b128 v[50:53], v159 offset:38912
	v_pk_fma_f32 v[78:79], v[78:79], s[36:37], v[82:83] op_sel_hi:[1,0,1]
	v_pk_fma_f32 v[80:81], v[80:81], s[36:37], v[84:85] op_sel_hi:[1,0,1]
	v_pk_fma_f32 v[70:71], v[70:71], s[36:37], v[86:87] op_sel_hi:[1,0,1]
	v_pk_fma_f32 v[72:73], v[72:73], s[36:37], v[88:89] op_sel_hi:[1,0,1]
	v_pk_fma_f32 v[62:63], v[62:63], s[36:37], v[90:91] op_sel_hi:[1,0,1]
	v_pk_fma_f32 v[64:65], v[64:65], s[36:37], v[92:93] op_sel_hi:[1,0,1]
	v_pk_fma_f32 v[54:55], v[54:55], s[36:37], v[94:95] op_sel_hi:[1,0,1]
	v_pk_fma_f32 v[56:57], v[56:57], s[36:37], v[96:97] op_sel_hi:[1,0,1]
	v_max3_f32 v116, v78, v79, v80
	v_max3_f32 v116, v116, v81, v70
	v_max3_f32 v116, v116, v71, v72
	v_max3_f32 v116, v116, v73, v62
	v_max3_f32 v116, v116, v63, v64
	v_max3_f32 v116, v116, v65, v54
	v_max3_f32 v116, v116, v55, v56
	v_max3_f32 v116, v116, v57, s29
	v_mov_b32_e32 v117, v116
	s_nop 1
	v_permlane16_swap_b32_e32 v116, v117
	v_max_f32_e32 v116, v116, v117
	v_mov_b32_e32 v117, v116
	s_nop 1
	v_permlane32_swap_b32_e32 v116, v117
	v_max_f32_e32 v116, v116, v117
	v_max_f32_e32 v121, v166, v116
	v_sub_f32_e32 v118, v166, v121
	v_exp_f32_e32 v118, v118
	v_mov_b32_e32 v166, v121
	v_mov_b32_e32 v120, v121
	v_pk_mul_f32 v[46:47], v[46:47], v[118:119] op_sel_hi:[1,0]
	v_pk_mul_f32 v[48:49], v[48:49], v[118:119] op_sel_hi:[1,0]
	v_pk_mul_f32 v[42:43], v[42:43], v[118:119] op_sel_hi:[1,0]
	v_pk_mul_f32 v[44:45], v[44:45], v[118:119] op_sel_hi:[1,0]
	v_pk_mul_f32 v[38:39], v[38:39], v[118:119] op_sel_hi:[1,0]
	v_pk_mul_f32 v[40:41], v[40:41], v[118:119] op_sel_hi:[1,0]
	v_pk_mul_f32 v[34:35], v[34:35], v[118:119] op_sel_hi:[1,0]
	v_pk_mul_f32 v[36:37], v[36:37], v[118:119] op_sel_hi:[1,0]
	v_pk_add_f32 v[78:79], v[78:79], v[120:121] op_sel_hi:[1,0] neg_lo:[0,1] neg_hi:[0,1]
	v_pk_add_f32 v[80:81], v[80:81], v[120:121] op_sel_hi:[1,0] neg_lo:[0,1] neg_hi:[0,1]
	v_pk_add_f32 v[70:71], v[70:71], v[120:121] op_sel_hi:[1,0] neg_lo:[0,1] neg_hi:[0,1]
	v_pk_add_f32 v[72:73], v[72:73], v[120:121] op_sel_hi:[1,0] neg_lo:[0,1] neg_hi:[0,1]
	v_pk_add_f32 v[62:63], v[62:63], v[120:121] op_sel_hi:[1,0] neg_lo:[0,1] neg_hi:[0,1]
	v_pk_add_f32 v[64:65], v[64:65], v[120:121] op_sel_hi:[1,0] neg_lo:[0,1] neg_hi:[0,1]
	v_pk_add_f32 v[54:55], v[54:55], v[120:121] op_sel_hi:[1,0] neg_lo:[0,1] neg_hi:[0,1]
	v_pk_add_f32 v[56:57], v[56:57], v[120:121] op_sel_hi:[1,0] neg_lo:[0,1] neg_hi:[0,1]
	v_exp_f32_e32 v78, v78
	v_exp_f32_e32 v79, v79
	v_exp_f32_e32 v80, v80
	v_exp_f32_e32 v81, v81
	v_exp_f32_e32 v70, v70
	v_exp_f32_e32 v71, v71
	v_exp_f32_e32 v72, v72
	v_exp_f32_e32 v73, v73
	v_exp_f32_e32 v62, v62
	v_exp_f32_e32 v63, v63
	v_exp_f32_e32 v64, v64
	v_exp_f32_e32 v65, v65
	v_exp_f32_e32 v54, v54
	v_exp_f32_e32 v55, v55
	v_exp_f32_e32 v56, v56
	v_exp_f32_e32 v57, v57
	s_nop 0
	v_pk_add_f32 v[82:83], v[78:79], v[80:81]
	v_pk_add_f32 v[84:85], v[70:71], v[72:73]
	v_pk_add_f32 v[86:87], v[62:63], v[64:65]
	v_pk_add_f32 v[88:89], v[54:55], v[56:57]
	v_pk_add_f32 v[82:83], v[82:83], v[84:85]
	v_pk_add_f32 v[86:87], v[86:87], v[88:89]
	s_nop 0
	v_pk_add_f32 v[82:83], v[82:83], v[86:87]
	s_nop 0
	v_add_f32_e32 v82, v82, v83
	v_fma_f32 v160, v160, v118, v82
	v_cvt_pk_bf16_f32 v73, v72, v73
	v_cvt_pk_bf16_f32 v72, v70, v71
	v_cvt_pk_bf16_f32 v71, v80, v81
	v_cvt_pk_bf16_f32 v70, v78, v79
	v_cvt_pk_bf16_f32 v62, v62, v63
	v_cvt_pk_bf16_f32 v63, v64, v65
	v_cvt_pk_bf16_f32 v64, v54, v55
	v_cvt_pk_bf16_f32 v65, v56, v57
	v_add_u32_e32 v115, 0xfbc, v114
	s_waitcnt lgkmcnt(0)
	ds_read2_b32 v[82:83], v115 offset1:1
	ds_read2_b32 v[84:85], v115 offset0:2 offset1:3
	ds_read2_b32 v[86:87], v115 offset0:16 offset1:17
	ds_read2_b32 v[88:89], v115 offset0:18 offset1:19
	ds_read2_b32 v[90:91], v115 offset0:32 offset1:33
	ds_read2_b32 v[92:93], v115 offset0:34 offset1:35
	ds_read2_b32 v[94:95], v115 offset0:48 offset1:49
	ds_read2_b32 v[96:97], v115 offset0:50 offset1:51
	v_mfma_f32_16x16x32_bf16 v[98:101], v[98:101], v[10:13], 0
	v_mfma_f32_16x16x32_bf16 v[102:105], v[102:105], v[10:13], 0
	v_mfma_f32_16x16x32_bf16 v[106:109], v[106:109], v[10:13], 0
	v_mfma_f32_16x16x32_bf16 v[110:113], v[110:113], v[10:13], 0
	v_mfma_f32_16x16x32_bf16 v[98:101], v[74:77], v[14:17], v[98:101]
	v_mfma_f32_16x16x32_bf16 v[102:105], v[66:69], v[14:17], v[102:105]
	v_mfma_f32_16x16x32_bf16 v[106:109], v[58:61], v[14:17], v[106:109]
	v_mfma_f32_16x16x32_bf16 v[110:113], v[50:53], v[14:17], v[110:113]
	s_waitcnt lgkmcnt(0)
	s_nop 6
	v_pk_fma_f32 v[98:99], v[98:99], s[36:37], v[82:83] op_sel_hi:[1,0,1]
	v_pk_fma_f32 v[100:101], v[100:101], s[36:37], v[84:85] op_sel_hi:[1,0,1]
	v_pk_fma_f32 v[102:103], v[102:103], s[36:37], v[86:87] op_sel_hi:[1,0,1]
	v_pk_fma_f32 v[104:105], v[104:105], s[36:37], v[88:89] op_sel_hi:[1,0,1]
	v_pk_fma_f32 v[106:107], v[106:107], s[36:37], v[90:91] op_sel_hi:[1,0,1]
	v_pk_fma_f32 v[108:109], v[108:109], s[36:37], v[92:93] op_sel_hi:[1,0,1]
	v_pk_fma_f32 v[110:111], v[110:111], s[36:37], v[94:95] op_sel_hi:[1,0,1]
	v_pk_fma_f32 v[112:113], v[112:113], s[36:37], v[96:97] op_sel_hi:[1,0,1]
	v_max3_f32 v116, v98, v99, v100
	v_max3_f32 v116, v116, v101, v102
	v_max3_f32 v116, v116, v103, v104
	v_max3_f32 v116, v116, v105, v106
	v_max3_f32 v116, v116, v107, v108
	v_max3_f32 v116, v116, v109, v110
	v_max3_f32 v116, v116, v111, v112
	v_max3_f32 v116, v116, v113, s29
	v_mov_b32_e32 v117, v116
	s_nop 1
	v_permlane16_swap_b32_e32 v116, v117
	v_max_f32_e32 v116, v116, v117
	v_mov_b32_e32 v117, v116
	s_nop 1
	v_permlane32_swap_b32_e32 v116, v117
	v_max_f32_e32 v116, v116, v117
	v_max_f32_e32 v121, v167, v116
	v_sub_f32_e32 v118, v167, v121
	v_exp_f32_e32 v118, v118
	v_mov_b32_e32 v167, v121
	v_mov_b32_e32 v120, v121
	v_pk_mul_f32 v[30:31], v[30:31], v[118:119] op_sel_hi:[1,0]
	v_pk_mul_f32 v[32:33], v[32:33], v[118:119] op_sel_hi:[1,0]
	v_pk_mul_f32 v[26:27], v[26:27], v[118:119] op_sel_hi:[1,0]
	v_pk_mul_f32 v[28:29], v[28:29], v[118:119] op_sel_hi:[1,0]
	v_pk_mul_f32 v[22:23], v[22:23], v[118:119] op_sel_hi:[1,0]
	v_pk_mul_f32 v[24:25], v[24:25], v[118:119] op_sel_hi:[1,0]
	v_pk_mul_f32 v[18:19], v[18:19], v[118:119] op_sel_hi:[1,0]
	v_pk_mul_f32 v[20:21], v[20:21], v[118:119] op_sel_hi:[1,0]
	v_pk_add_f32 v[98:99], v[98:99], v[120:121] op_sel_hi:[1,0] neg_lo:[0,1] neg_hi:[0,1]
	v_pk_add_f32 v[100:101], v[100:101], v[120:121] op_sel_hi:[1,0] neg_lo:[0,1] neg_hi:[0,1]
	v_pk_add_f32 v[102:103], v[102:103], v[120:121] op_sel_hi:[1,0] neg_lo:[0,1] neg_hi:[0,1]
	v_pk_add_f32 v[104:105], v[104:105], v[120:121] op_sel_hi:[1,0] neg_lo:[0,1] neg_hi:[0,1]
	v_pk_add_f32 v[106:107], v[106:107], v[120:121] op_sel_hi:[1,0] neg_lo:[0,1] neg_hi:[0,1]
	v_pk_add_f32 v[108:109], v[108:109], v[120:121] op_sel_hi:[1,0] neg_lo:[0,1] neg_hi:[0,1]
	v_pk_add_f32 v[110:111], v[110:111], v[120:121] op_sel_hi:[1,0] neg_lo:[0,1] neg_hi:[0,1]
	v_pk_add_f32 v[112:113], v[112:113], v[120:121] op_sel_hi:[1,0] neg_lo:[0,1] neg_hi:[0,1]
	v_exp_f32_e32 v98, v98
	v_exp_f32_e32 v99, v99
	v_exp_f32_e32 v100, v100
	v_exp_f32_e32 v101, v101
	v_exp_f32_e32 v102, v102
	v_exp_f32_e32 v103, v103
	v_exp_f32_e32 v104, v104
	v_exp_f32_e32 v105, v105
	v_exp_f32_e32 v106, v106
	v_exp_f32_e32 v107, v107
	v_exp_f32_e32 v108, v108
	v_exp_f32_e32 v109, v109
	v_exp_f32_e32 v110, v110
	v_exp_f32_e32 v111, v111
	v_exp_f32_e32 v112, v112
	v_exp_f32_e32 v113, v113
	s_nop 0
	v_pk_add_f32 v[82:83], v[98:99], v[100:101]
	v_pk_add_f32 v[84:85], v[102:103], v[104:105]
	v_pk_add_f32 v[86:87], v[106:107], v[108:109]
	v_pk_add_f32 v[88:89], v[110:111], v[112:113]
	v_pk_add_f32 v[82:83], v[82:83], v[84:85]
	v_pk_add_f32 v[86:87], v[86:87], v[88:89]
	s_nop 0
	v_pk_add_f32 v[82:83], v[82:83], v[86:87]
	s_nop 0
	v_add_f32_e32 v82, v82, v83
	v_fma_f32 v161, v161, v118, v82
	v_cvt_pk_bf16_f32 v105, v104, v105
	v_cvt_pk_bf16_f32 v104, v102, v103
	v_cvt_pk_bf16_f32 v103, v100, v101
	v_cvt_pk_bf16_f32 v102, v98, v99
	v_cvt_pk_bf16_f32 v106, v106, v107
	v_cvt_pk_bf16_f32 v107, v108, v109
	v_cvt_pk_bf16_f32 v108, v110, v111
	v_cvt_pk_bf16_f32 v109, v112, v113

.LBB0_419:
	s_cmp_eq_u32 s13, s12
	s_cbranch_scc1 .LBB0_418
	s_or_b32 s6, s13, s5
	s_ff1_i32_b64 s18, s[8:9]
	s_lshl_b32 s6, s6, 14
	s_and_b32 s6, s6, 0xc000
	s_lshl_b32 s14, s18, 6
	s_add_i32 s13, s6, 0
	s_or_b32 s16, s14, 63
	s_mov_b64 s[6:7], -1
	s_cmp_ge_i32 s16, s1
	v_lshrrev_b64 v[162:163], s18, v[38:39]
	v_lshrrev_b64 v[164:165], s18, v[40:41]
	s_cbranch_scc0 .LBB0_439
	s_cmp_le_i32 s16, s2
	s_cselect_b64 s[6:7], -1, 0
	s_cmp_gt_i32 s14, s4
	v_and_b32_e32 v0, 1, v164
	s_cselect_b64 s[18:19], -1, 0
	v_cmp_eq_u32_e64 s[42:43], 1, v0
	v_and_b32_e32 v0, 1, v162
	s_and_b64 s[18:19], s[6:7], s[18:19]
	v_cmp_eq_u32_e64 s[44:45], 1, v0
	s_andn2_b64 vcc, exec, s[18:19]
	s_or_b64 s[18:19], s[44:45], s[42:43]
	s_mov_b64 s[6:7], -1
	v_cndmask_b32_e64 v139, 0, 1, s[18:19]
	s_cbranch_vccz .LBB0_430
	v_cmp_ne_u32_e32 vcc, 0, v139
	s_cbranch_vccz .Lsel_fast
	v_add_u32_e32 v54, s13, v196
	v_cmp_ne_u32_e32 vcc, 0, v0
	v_sub_u32_e32 v0, s14, v140
	v_add_u32_e32 v62, v54, v194
	v_add_u32_e32 v89, v54, v195
	v_lshl_add_u32 v0, v0, 2, v216
	s_cbranch_vccz .Lp0_skip0
	v_add_u32_e32 v63, 0xffc, v0
	ds_read_b128 v[54:57], v62 offset:16384
	ds_read_b128 v[58:61], v62 offset:18432
	ds_read_b128 v[64:67], v62 offset:20480
	ds_read_b128 v[68:71], v89 offset:16384
	ds_read_b128 v[72:75], v62 offset:22528
	ds_read2_b32 v[90:91], v63 offset1:1
	ds_read2_b32 v[92:93], v63 offset0:2 offset1:3
	ds_read2_b32 v[94:95], v63 offset0:16 offset1:17
	ds_read2_b32 v[96:97], v63 offset0:18 offset1:19
	ds_read2_b32 v[98:99], v63 offset0:32 offset1:33
	ds_read2_b32 v[100:101], v63 offset0:34 offset1:35
	ds_read2_b32 v[154:155], v63 offset0:48 offset1:49
	ds_read2_b32 v[156:157], v63 offset0:50 offset1:51
	s_waitcnt lgkmcnt(8)
	v_mfma_f32_16x16x32_bf16 v[54:57], v[54:57], v[2:5], 0
	v_mfma_f32_16x16x32_bf16 v[58:61], v[58:61], v[2:5], 0
	v_mfma_f32_16x16x32_bf16 v[54:57], v[68:71], v[6:9], v[54:57]
	ds_read_b128 v[68:71], v89 offset:18432
	ds_read_b128 v[76:79], v89 offset:20480
	v_mfma_f32_16x16x32_bf16 v[64:67], v[64:67], v[2:5], 0
	v_mfma_f32_16x16x32_bf16 v[84:87], v[72:75], v[2:5], 0
	s_waitcnt lgkmcnt(0)
	v_mfma_f32_16x16x32_bf16 v[58:61], v[68:71], v[6:9], v[58:61]
	ds_read_b128 v[68:71], v89 offset:22528
	v_mfma_f32_16x16x32_bf16 v[64:67], v[76:79], v[6:9], v[64:67]
	s_waitcnt lgkmcnt(0)
	v_mfma_f32_16x16x32_bf16 v[84:87], v[68:71], v[6:9], v[84:87]
	v_pk_fma_f32 v[54:55], v[54:55], s[36:37], v[90:91] op_sel_hi:[1,0,1]
	v_pk_fma_f32 v[56:57], v[56:57], s[36:37], v[92:93] op_sel_hi:[1,0,1]
	s_nop 1
	v_pk_fma_f32 v[58:59], v[58:59], s[36:37], v[94:95] op_sel_hi:[1,0,1]
	v_pk_fma_f32 v[60:61], v[60:61], s[36:37], v[96:97] op_sel_hi:[1,0,1]
	v_pk_fma_f32 v[64:65], v[64:65], s[36:37], v[98:99] op_sel_hi:[1,0,1]
	v_pk_fma_f32 v[66:67], v[66:67], s[36:37], v[100:101] op_sel_hi:[1,0,1]
	v_pk_fma_f32 v[84:85], v[84:85], s[36:37], v[154:155] op_sel_hi:[1,0,1]
	v_pk_fma_f32 v[86:87], v[86:87], s[36:37], v[156:157] op_sel_hi:[1,0,1]
	v_or_b32_e32 v83, s14, v197
	v_sub_u32_e32 v88, v140, v83
	v_cmp_le_i32_e64 s[6:7], 0, v88
	v_cmp_le_i32_e64 s[18:19], 1, v88
	v_cmp_le_i32_e64 s[98:99], 2, v88
	v_cmp_le_i32_e64 s[100:101], 3, v88
	v_cndmask_b32_e64 v54, v148, v54, s[6:7]
	v_cndmask_b32_e64 v55, v148, v55, s[18:19]
	v_cndmask_b32_e64 v56, v148, v56, s[98:99]
	v_cndmask_b32_e64 v57, v148, v57, s[100:101]
	v_cmp_le_i32_e64 s[6:7], 16, v88
	v_cmp_le_i32_e64 s[18:19], 17, v88
	v_cmp_le_i32_e64 s[98:99], 18, v88
	v_cmp_le_i32_e64 s[100:101], 19, v88
	v_cndmask_b32_e64 v58, v148, v58, s[6:7]
	v_cndmask_b32_e64 v59, v148, v59, s[18:19]
	v_cndmask_b32_e64 v60, v148, v60, s[98:99]
	v_cndmask_b32_e64 v61, v148, v61, s[100:101]
	v_cmp_le_i32_e64 s[6:7], 32, v88
	v_cmp_le_i32_e64 s[18:19], 33, v88
	v_cmp_le_i32_e64 s[98:99], 34, v88
	v_cmp_le_i32_e64 s[100:101], 35, v88
	v_cndmask_b32_e64 v64, v148, v64, s[6:7]
	v_cndmask_b32_e64 v65, v148, v65, s[18:19]
	v_cndmask_b32_e64 v66, v148, v66, s[98:99]
	v_cndmask_b32_e64 v67, v148, v67, s[100:101]
	v_cmp_le_i32_e64 s[6:7], 48, v88
	v_cmp_le_i32_e64 s[18:19], 49, v88
	v_cmp_le_i32_e64 s[98:99], 50, v88
	v_cmp_le_i32_e64 s[100:101], 51, v88
	v_cndmask_b32_e64 v84, v148, v84, s[6:7]
	v_cndmask_b32_e64 v85, v148, v85, s[18:19]
	v_cndmask_b32_e64 v86, v148, v86, s[98:99]
	v_cndmask_b32_e64 v87, v148, v87, s[100:101]
	v_max3_f32 v63, v54, v55, v56
	v_max3_f32 v63, v63, v57, v58
	v_max3_f32 v63, v63, v59, v60
	v_max3_f32 v63, v63, v61, v64
	v_max3_f32 v63, v63, v65, v66
	v_max3_f32 v63, v63, v67, v84
	v_max3_f32 v63, v63, v85, v86
	v_max3_f32 v63, v63, v87, s29
	v_mov_b32_e32 v68, v63
	s_nop 1
	v_permlane16_swap_b32_e32 v63, v68
	v_max_f32_e32 v63, v63, v68
	v_mov_b32_e32 v68, v63
	s_nop 1
	v_permlane32_swap_b32_e32 v63, v68
	v_max_f32_e32 v63, v63, v68
	v_cndmask_b32_e64 v63, v148, v63, s[44:45]
	v_max_f32_e32 v68, v160, v63
	v_sub_f32_e32 v69, v160, v68
	v_exp_f32_e32 v70, v69
	v_cndmask_b32_e64 v82, v209, v68, s[44:45]
	v_mov_b32_e32 v160, v68
	v_pk_mul_f32 v[36:37], v[36:37], v[70:71] op_sel_hi:[1,0]
	v_pk_mul_f32 v[34:35], v[34:35], v[70:71] op_sel_hi:[1,0]
	v_pk_mul_f32 v[48:49], v[48:49], v[70:71] op_sel_hi:[1,0]
	v_pk_mul_f32 v[46:47], v[46:47], v[70:71] op_sel_hi:[1,0]
	v_pk_mul_f32 v[44:45], v[44:45], v[70:71] op_sel_hi:[1,0]
	v_pk_mul_f32 v[42:43], v[42:43], v[70:71] op_sel_hi:[1,0]
	v_pk_mul_f32 v[52:53], v[52:53], v[70:71] op_sel_hi:[1,0]
	v_pk_mul_f32 v[50:51], v[50:51], v[70:71] op_sel_hi:[1,0]
	v_pk_add_f32 v[54:55], v[54:55], v[82:83] op_sel_hi:[1,0] neg_lo:[0,1] neg_hi:[0,1]
	v_pk_add_f32 v[56:57], v[56:57], v[82:83] op_sel_hi:[1,0] neg_lo:[0,1] neg_hi:[0,1]
	v_pk_add_f32 v[58:59], v[58:59], v[82:83] op_sel_hi:[1,0] neg_lo:[0,1] neg_hi:[0,1]
	v_pk_add_f32 v[60:61], v[60:61], v[82:83] op_sel_hi:[1,0] neg_lo:[0,1] neg_hi:[0,1]
	v_pk_add_f32 v[64:65], v[64:65], v[82:83] op_sel_hi:[1,0] neg_lo:[0,1] neg_hi:[0,1]
	v_pk_add_f32 v[66:67], v[66:67], v[82:83] op_sel_hi:[1,0] neg_lo:[0,1] neg_hi:[0,1]
	v_pk_add_f32 v[84:85], v[84:85], v[82:83] op_sel_hi:[1,0] neg_lo:[0,1] neg_hi:[0,1]
	v_pk_add_f32 v[86:87], v[86:87], v[82:83] op_sel_hi:[1,0] neg_lo:[0,1] neg_hi:[0,1]
	v_exp_f32_e32 v54, v54
	v_exp_f32_e32 v55, v55
	v_exp_f32_e32 v56, v56
	v_exp_f32_e32 v57, v57
	v_exp_f32_e32 v58, v58
	v_exp_f32_e32 v59, v59
	v_exp_f32_e32 v60, v60
	v_exp_f32_e32 v61, v61
	v_exp_f32_e32 v64, v64
	v_exp_f32_e32 v65, v65
	v_exp_f32_e32 v66, v66
	v_exp_f32_e32 v67, v67
	v_exp_f32_e32 v84, v84
	v_exp_f32_e32 v85, v85
	v_exp_f32_e32 v86, v86
	v_exp_f32_e32 v87, v87
	s_nop 0
	v_pk_add_f32 v[72:73], v[54:55], v[56:57]
	v_pk_add_f32 v[74:75], v[58:59], v[60:61]
	v_pk_add_f32 v[76:77], v[64:65], v[66:67]
	v_pk_add_f32 v[78:79], v[84:85], v[86:87]
	v_pk_add_f32 v[72:73], v[72:73], v[74:75]
	v_pk_add_f32 v[76:77], v[76:77], v[78:79]
	s_nop 0
	v_pk_add_f32 v[72:73], v[72:73], v[76:77]
	s_nop 0
	v_add_f32_e32 v72, v72, v73
	v_fma_f32 v144, v144, v70, v72
	v_cvt_pk_bf16_f32 v61, v60, v61
	v_cvt_pk_bf16_f32 v60, v58, v59
	v_cvt_pk_bf16_f32 v59, v56, v57
	v_cvt_pk_bf16_f32 v58, v54, v55
	v_cvt_pk_bf16_f32 v54, v64, v65
	v_cvt_pk_bf16_f32 v55, v66, v67
	v_cvt_pk_bf16_f32 v56, v84, v85
	v_cvt_pk_bf16_f32 v57, v86, v87
	v_cndmask_b32_e64 v63, 0, 1, s[42:43]
	v_cmp_ne_u32_e32 vcc, 0, v63
	s_cbranch_vccz .LBB0_445
.Lp0_cb1:
	v_add_u32_e32 v88, 0xfec, v0
	ds_read_b128 v[64:67], v62 offset:16384
	ds_read_b128 v[68:71], v62 offset:18432
	ds_read_b128 v[72:75], v89 offset:16384
	ds_read_b128 v[76:79], v89 offset:18432
	ds_read2_b32 v[90:91], v88 offset1:1
	ds_read2_b32 v[92:93], v88 offset0:2 offset1:3
	ds_read2_b32 v[94:95], v88 offset0:16 offset1:17
	ds_read2_b32 v[96:97], v88 offset0:18 offset1:19
	ds_read2_b32 v[98:99], v88 offset0:32 offset1:33
	ds_read2_b32 v[100:101], v88 offset0:34 offset1:35
	ds_read2_b32 v[154:155], v88 offset0:48 offset1:49
	ds_read2_b32 v[156:157], v88 offset0:50 offset1:51
	s_waitcnt lgkmcnt(8)
	v_mfma_f32_16x16x32_bf16 v[64:67], v[64:67], v[10:13], 0
	v_mfma_f32_16x16x32_bf16 v[68:71], v[68:71], v[10:13], 0
	v_mfma_f32_16x16x32_bf16 v[64:67], v[72:75], v[14:17], v[64:67]
	ds_read_b128 v[72:75], v62 offset:20480
	v_mfma_f32_16x16x32_bf16 v[68:71], v[76:79], v[14:17], v[68:71]
	ds_read_b128 v[76:79], v89 offset:20480
	ds_read_b128 v[80:83], v62 offset:22528
	ds_read_b128 v[84:87], v89 offset:22528
	s_waitcnt lgkmcnt(0)
	v_mfma_f32_16x16x32_bf16 v[72:75], v[72:75], v[10:13], 0
	v_mfma_f32_16x16x32_bf16 v[80:83], v[80:83], v[10:13], 0
	v_mfma_f32_16x16x32_bf16 v[72:75], v[76:79], v[14:17], v[72:75]
	v_mfma_f32_16x16x32_bf16 v[80:83], v[84:87], v[14:17], v[80:83]
	v_pk_fma_f32 v[64:65], v[64:65], s[36:37], v[90:91] op_sel_hi:[1,0,1]
	v_pk_fma_f32 v[66:67], v[66:67], s[36:37], v[92:93] op_sel_hi:[1,0,1]
	v_pk_fma_f32 v[68:69], v[68:69], s[36:37], v[94:95] op_sel_hi:[1,0,1]
	v_pk_fma_f32 v[70:71], v[70:71], s[36:37], v[96:97] op_sel_hi:[1,0,1]
	s_nop 3
	v_pk_fma_f32 v[72:73], v[72:73], s[36:37], v[98:99] op_sel_hi:[1,0,1]
	v_pk_fma_f32 v[74:75], v[74:75], s[36:37], v[100:101] op_sel_hi:[1,0,1]
	v_pk_fma_f32 v[80:81], v[80:81], s[36:37], v[154:155] op_sel_hi:[1,0,1]
	v_pk_fma_f32 v[82:83], v[82:83], s[36:37], v[156:157] op_sel_hi:[1,0,1]
	v_or_b32_e32 v79, s14, v197
	v_sub_u32_e32 v88, v142, v79
	v_cmp_le_i32_e64 s[6:7], 0, v88
	v_cmp_le_i32_e64 s[18:19], 1, v88
	v_cmp_le_i32_e64 s[98:99], 2, v88
	v_cmp_le_i32_e64 s[100:101], 3, v88
	v_cndmask_b32_e64 v64, v148, v64, s[6:7]
	v_cndmask_b32_e64 v65, v148, v65, s[18:19]
	v_cndmask_b32_e64 v66, v148, v66, s[98:99]
	v_cndmask_b32_e64 v67, v148, v67, s[100:101]
	v_cmp_le_i32_e64 s[6:7], 16, v88
	v_cmp_le_i32_e64 s[18:19], 17, v88
	v_cmp_le_i32_e64 s[98:99], 18, v88
	v_cmp_le_i32_e64 s[100:101], 19, v88
	v_cndmask_b32_e64 v68, v148, v68, s[6:7]
	v_cndmask_b32_e64 v69, v148, v69, s[18:19]
	v_cndmask_b32_e64 v70, v148, v70, s[98:99]
	v_cndmask_b32_e64 v71, v148, v71, s[100:101]
	v_cmp_le_i32_e64 s[6:7], 32, v88
	v_cmp_le_i32_e64 s[18:19], 33, v88
	v_cmp_le_i32_e64 s[98:99], 34, v88
	v_cmp_le_i32_e64 s[100:101], 35, v88
	v_cndmask_b32_e64 v72, v148, v72, s[6:7]
	v_cndmask_b32_e64 v73, v148, v73, s[18:19]
	v_cndmask_b32_e64 v74, v148, v74, s[98:99]
	v_cndmask_b32_e64 v75, v148, v75, s[100:101]
	v_cmp_le_i32_e64 s[6:7], 48, v88
	v_cmp_le_i32_e64 s[18:19], 49, v88
	v_cmp_le_i32_e64 s[98:99], 50, v88
	v_cmp_le_i32_e64 s[100:101], 51, v88
	v_cndmask_b32_e64 v80, v148, v80, s[6:7]
	v_cndmask_b32_e64 v81, v148, v81, s[18:19]
	v_cndmask_b32_e64 v82, v148, v82, s[98:99]
	v_cndmask_b32_e64 v83, v148, v83, s[100:101]
	v_max3_f32 v76, v64, v65, v66
	v_max3_f32 v76, v76, v67, v68
	v_max3_f32 v76, v76, v69, v70
	v_max3_f32 v76, v76, v71, v72
	v_max3_f32 v76, v76, v73, v74
	v_max3_f32 v76, v76, v75, v80
	v_max3_f32 v76, v76, v81, v82
	v_max3_f32 v76, v76, v83, s29
	v_mov_b32_e32 v77, v76
	s_nop 1
	v_permlane16_swap_b32_e32 v76, v77
	v_max_f32_e32 v76, v76, v77
	v_mov_b32_e32 v77, v76
	s_nop 1
	v_permlane32_swap_b32_e32 v76, v77
	v_max_f32_e32 v76, v76, v77
	v_cndmask_b32_e64 v76, v148, v76, s[42:43]
	v_max_f32_e32 v77, v161, v76
	v_sub_f32_e32 v0, v161, v77
	v_exp_f32_e32 v0, v0
	v_cndmask_b32_e64 v78, v209, v77, s[42:43]
	v_mov_b32_e32 v161, v77
	v_pk_mul_f32 v[32:33], v[32:33], v[0:1] op_sel_hi:[1,0]
	v_pk_mul_f32 v[30:31], v[30:31], v[0:1] op_sel_hi:[1,0]
	v_pk_mul_f32 v[28:29], v[28:29], v[0:1] op_sel_hi:[1,0]
	v_pk_mul_f32 v[26:27], v[26:27], v[0:1] op_sel_hi:[1,0]
	v_pk_mul_f32 v[24:25], v[24:25], v[0:1] op_sel_hi:[1,0]
	v_pk_mul_f32 v[22:23], v[22:23], v[0:1] op_sel_hi:[1,0]
	v_pk_mul_f32 v[20:21], v[20:21], v[0:1] op_sel_hi:[1,0]
	v_pk_mul_f32 v[18:19], v[18:19], v[0:1] op_sel_hi:[1,0]
	v_pk_add_f32 v[64:65], v[64:65], v[78:79] op_sel_hi:[1,0] neg_lo:[0,1] neg_hi:[0,1]
	v_pk_add_f32 v[66:67], v[66:67], v[78:79] op_sel_hi:[1,0] neg_lo:[0,1] neg_hi:[0,1]
	v_pk_add_f32 v[68:69], v[68:69], v[78:79] op_sel_hi:[1,0] neg_lo:[0,1] neg_hi:[0,1]
	v_pk_add_f32 v[70:71], v[70:71], v[78:79] op_sel_hi:[1,0] neg_lo:[0,1] neg_hi:[0,1]
	v_pk_add_f32 v[72:73], v[72:73], v[78:79] op_sel_hi:[1,0] neg_lo:[0,1] neg_hi:[0,1]
	v_pk_add_f32 v[74:75], v[74:75], v[78:79] op_sel_hi:[1,0] neg_lo:[0,1] neg_hi:[0,1]
	v_pk_add_f32 v[80:81], v[80:81], v[78:79] op_sel_hi:[1,0] neg_lo:[0,1] neg_hi:[0,1]
	v_pk_add_f32 v[82:83], v[82:83], v[78:79] op_sel_hi:[1,0] neg_lo:[0,1] neg_hi:[0,1]
	v_exp_f32_e32 v64, v64
	v_exp_f32_e32 v65, v65
	v_exp_f32_e32 v66, v66
	v_exp_f32_e32 v67, v67
	v_exp_f32_e32 v68, v68
	v_exp_f32_e32 v69, v69
	v_exp_f32_e32 v70, v70
	v_exp_f32_e32 v71, v71
	v_exp_f32_e32 v72, v72
	v_exp_f32_e32 v73, v73
	v_exp_f32_e32 v74, v74
	v_exp_f32_e32 v75, v75
	v_exp_f32_e32 v80, v80
	v_exp_f32_e32 v81, v81
	v_exp_f32_e32 v82, v82
	v_exp_f32_e32 v83, v83
	s_nop 0
	v_pk_add_f32 v[84:85], v[64:65], v[66:67]
	v_pk_add_f32 v[86:87], v[68:69], v[70:71]
	v_pk_add_f32 v[76:77], v[72:73], v[74:75]
	v_pk_add_f32 v[78:79], v[80:81], v[82:83]
	v_pk_add_f32 v[84:85], v[84:85], v[86:87]
	v_pk_add_f32 v[76:77], v[76:77], v[78:79]
	s_nop 0
	v_pk_add_f32 v[84:85], v[84:85], v[76:77]
	s_nop 0
	v_add_f32_e32 v84, v84, v85
	v_fma_f32 v145, v145, v0, v84
	v_cvt_pk_bf16_f32 v67, v66, v67
	v_cvt_pk_bf16_f32 v66, v64, v65
	v_cvt_pk_bf16_f32 v68, v68, v69
	v_cvt_pk_bf16_f32 v69, v70, v71
	v_cvt_pk_bf16_f32 v62, v72, v73
	v_cvt_pk_bf16_f32 v63, v74, v75
	v_cvt_pk_bf16_f32 v64, v80, v81
	v_cvt_pk_bf16_f32 v65, v82, v83
	s_branch .LBB0_446

.LBB0_430:
	s_andn2_b64 vcc, exec, s[6:7]
	s_cbranch_vccnz .LBB0_438
	v_cmp_ne_u32_e32 vcc, 0, v139
	s_cbranch_vccz .Lsel_fast
	v_add_u32_e32 v54, s13, v196
	v_cmp_ne_u32_e32 vcc, 0, v0
	v_sub_u32_e32 v0, s14, v140
	v_add_u32_e32 v62, v54, v194
	v_add_u32_e32 v89, v54, v195
	v_lshl_add_u32 v0, v0, 2, v216
	s_cbranch_vccz .Lp1_skip0
	v_add_u32_e32 v63, 0xffc, v0
	ds_read_b128 v[54:57], v62 offset:16384
	ds_read_b128 v[58:61], v62 offset:18432
	ds_read_b128 v[64:67], v62 offset:20480
	ds_read_b128 v[68:71], v89 offset:16384
	ds_read_b128 v[72:75], v62 offset:22528
	ds_read2_b32 v[90:91], v63 offset1:1
	ds_read2_b32 v[92:93], v63 offset0:2 offset1:3
	ds_read2_b32 v[94:95], v63 offset0:16 offset1:17
	ds_read2_b32 v[96:97], v63 offset0:18 offset1:19
	ds_read2_b32 v[98:99], v63 offset0:32 offset1:33
	ds_read2_b32 v[100:101], v63 offset0:34 offset1:35
	ds_read2_b32 v[154:155], v63 offset0:48 offset1:49
	ds_read2_b32 v[156:157], v63 offset0:50 offset1:51
	s_waitcnt lgkmcnt(8)
	v_mfma_f32_16x16x32_bf16 v[54:57], v[54:57], v[2:5], 0
	v_mfma_f32_16x16x32_bf16 v[58:61], v[58:61], v[2:5], 0
	v_mfma_f32_16x16x32_bf16 v[54:57], v[68:71], v[6:9], v[54:57]
	ds_read_b128 v[68:71], v89 offset:18432
	ds_read_b128 v[76:79], v89 offset:20480
	v_mfma_f32_16x16x32_bf16 v[64:67], v[64:67], v[2:5], 0
	v_mfma_f32_16x16x32_bf16 v[84:87], v[72:75], v[2:5], 0
	s_waitcnt lgkmcnt(0)
	v_mfma_f32_16x16x32_bf16 v[58:61], v[68:71], v[6:9], v[58:61]
	ds_read_b128 v[68:71], v89 offset:22528
	v_mfma_f32_16x16x32_bf16 v[64:67], v[76:79], v[6:9], v[64:67]
	s_waitcnt lgkmcnt(0)
	v_mfma_f32_16x16x32_bf16 v[84:87], v[68:71], v[6:9], v[84:87]
	v_pk_fma_f32 v[54:55], v[54:55], s[36:37], v[90:91] op_sel_hi:[1,0,1]
	v_pk_fma_f32 v[56:57], v[56:57], s[36:37], v[92:93] op_sel_hi:[1,0,1]
	s_nop 1
	v_pk_fma_f32 v[58:59], v[58:59], s[36:37], v[94:95] op_sel_hi:[1,0,1]
	v_pk_fma_f32 v[60:61], v[60:61], s[36:37], v[96:97] op_sel_hi:[1,0,1]
	v_pk_fma_f32 v[64:65], v[64:65], s[36:37], v[98:99] op_sel_hi:[1,0,1]
	v_pk_fma_f32 v[66:67], v[66:67], s[36:37], v[100:101] op_sel_hi:[1,0,1]
	v_pk_fma_f32 v[84:85], v[84:85], s[36:37], v[154:155] op_sel_hi:[1,0,1]
	v_pk_fma_f32 v[86:87], v[86:87], s[36:37], v[156:157] op_sel_hi:[1,0,1]
	v_max3_f32 v63, v54, v55, v56
	v_max3_f32 v63, v63, v57, v58
	v_max3_f32 v63, v63, v59, v60
	v_max3_f32 v63, v63, v61, v64
	v_max3_f32 v63, v63, v65, v66
	v_max3_f32 v63, v63, v67, v84
	v_max3_f32 v63, v63, v85, v86
	v_max3_f32 v63, v63, v87, s29
	v_mov_b32_e32 v68, v63
	s_nop 1
	v_permlane16_swap_b32_e32 v63, v68
	v_max_f32_e32 v63, v63, v68
	v_mov_b32_e32 v68, v63
	s_nop 1
	v_permlane32_swap_b32_e32 v63, v68
	v_max_f32_e32 v63, v63, v68
	v_cndmask_b32_e64 v63, v148, v63, s[44:45]
	v_max_f32_e32 v68, v160, v63
	v_sub_f32_e32 v69, v160, v68
	v_exp_f32_e32 v70, v69
	v_cndmask_b32_e64 v82, v209, v68, s[44:45]
	v_mov_b32_e32 v160, v68
	v_pk_mul_f32 v[36:37], v[36:37], v[70:71] op_sel_hi:[1,0]
	v_pk_mul_f32 v[34:35], v[34:35], v[70:71] op_sel_hi:[1,0]
	v_pk_mul_f32 v[48:49], v[48:49], v[70:71] op_sel_hi:[1,0]
	v_pk_mul_f32 v[46:47], v[46:47], v[70:71] op_sel_hi:[1,0]
	v_pk_mul_f32 v[44:45], v[44:45], v[70:71] op_sel_hi:[1,0]
	v_pk_mul_f32 v[42:43], v[42:43], v[70:71] op_sel_hi:[1,0]
	v_pk_mul_f32 v[52:53], v[52:53], v[70:71] op_sel_hi:[1,0]
	v_pk_mul_f32 v[50:51], v[50:51], v[70:71] op_sel_hi:[1,0]
	v_pk_add_f32 v[54:55], v[54:55], v[82:83] op_sel_hi:[1,0] neg_lo:[0,1] neg_hi:[0,1]
	v_pk_add_f32 v[56:57], v[56:57], v[82:83] op_sel_hi:[1,0] neg_lo:[0,1] neg_hi:[0,1]
	v_pk_add_f32 v[58:59], v[58:59], v[82:83] op_sel_hi:[1,0] neg_lo:[0,1] neg_hi:[0,1]
	v_pk_add_f32 v[60:61], v[60:61], v[82:83] op_sel_hi:[1,0] neg_lo:[0,1] neg_hi:[0,1]
	v_pk_add_f32 v[64:65], v[64:65], v[82:83] op_sel_hi:[1,0] neg_lo:[0,1] neg_hi:[0,1]
	v_pk_add_f32 v[66:67], v[66:67], v[82:83] op_sel_hi:[1,0] neg_lo:[0,1] neg_hi:[0,1]
	v_pk_add_f32 v[84:85], v[84:85], v[82:83] op_sel_hi:[1,0] neg_lo:[0,1] neg_hi:[0,1]
	v_pk_add_f32 v[86:87], v[86:87], v[82:83] op_sel_hi:[1,0] neg_lo:[0,1] neg_hi:[0,1]
	v_exp_f32_e32 v54, v54
	v_exp_f32_e32 v55, v55
	v_exp_f32_e32 v56, v56
	v_exp_f32_e32 v57, v57
	v_exp_f32_e32 v58, v58
	v_exp_f32_e32 v59, v59
	v_exp_f32_e32 v60, v60
	v_exp_f32_e32 v61, v61
	v_exp_f32_e32 v64, v64
	v_exp_f32_e32 v65, v65
	v_exp_f32_e32 v66, v66
	v_exp_f32_e32 v67, v67
	v_exp_f32_e32 v84, v84
	v_exp_f32_e32 v85, v85
	v_exp_f32_e32 v86, v86
	v_exp_f32_e32 v87, v87
	s_nop 0
	v_pk_add_f32 v[72:73], v[54:55], v[56:57]
	v_pk_add_f32 v[74:75], v[58:59], v[60:61]
	v_pk_add_f32 v[76:77], v[64:65], v[66:67]
	v_pk_add_f32 v[78:79], v[84:85], v[86:87]
	v_pk_add_f32 v[72:73], v[72:73], v[74:75]
	v_pk_add_f32 v[76:77], v[76:77], v[78:79]
	s_nop 0
	v_pk_add_f32 v[72:73], v[72:73], v[76:77]
	s_nop 0
	v_add_f32_e32 v72, v72, v73
	v_fma_f32 v144, v144, v70, v72
	v_cvt_pk_bf16_f32 v61, v60, v61
	v_cvt_pk_bf16_f32 v60, v58, v59
	v_cvt_pk_bf16_f32 v59, v56, v57
	v_cvt_pk_bf16_f32 v58, v54, v55
	v_cvt_pk_bf16_f32 v54, v64, v65
	v_cvt_pk_bf16_f32 v55, v66, v67
	v_cvt_pk_bf16_f32 v56, v84, v85
	v_cvt_pk_bf16_f32 v57, v86, v87
	v_cndmask_b32_e64 v63, 0, 1, s[42:43]
	v_cmp_ne_u32_e32 vcc, 0, v63
	s_cbranch_vccz .LBB0_445
.Lp1_cb1:
	v_add_u32_e32 v88, 0xfec, v0
	ds_read_b128 v[64:67], v62 offset:16384
	ds_read_b128 v[68:71], v62 offset:18432
	ds_read_b128 v[72:75], v89 offset:16384
	ds_read_b128 v[76:79], v89 offset:18432
	ds_read2_b32 v[90:91], v88 offset1:1
	ds_read2_b32 v[92:93], v88 offset0:2 offset1:3
	ds_read2_b32 v[94:95], v88 offset0:16 offset1:17
	ds_read2_b32 v[96:97], v88 offset0:18 offset1:19
	ds_read2_b32 v[98:99], v88 offset0:32 offset1:33
	ds_read2_b32 v[100:101], v88 offset0:34 offset1:35
	ds_read2_b32 v[154:155], v88 offset0:48 offset1:49
	ds_read2_b32 v[156:157], v88 offset0:50 offset1:51
	s_waitcnt lgkmcnt(8)
	v_mfma_f32_16x16x32_bf16 v[64:67], v[64:67], v[10:13], 0
	v_mfma_f32_16x16x32_bf16 v[68:71], v[68:71], v[10:13], 0
	v_mfma_f32_16x16x32_bf16 v[64:67], v[72:75], v[14:17], v[64:67]
	ds_read_b128 v[72:75], v62 offset:20480
	v_mfma_f32_16x16x32_bf16 v[68:71], v[76:79], v[14:17], v[68:71]
	ds_read_b128 v[76:79], v89 offset:20480
	ds_read_b128 v[80:83], v62 offset:22528
	ds_read_b128 v[84:87], v89 offset:22528
	s_waitcnt lgkmcnt(0)
	v_mfma_f32_16x16x32_bf16 v[72:75], v[72:75], v[10:13], 0
	v_mfma_f32_16x16x32_bf16 v[80:83], v[80:83], v[10:13], 0
	v_mfma_f32_16x16x32_bf16 v[72:75], v[76:79], v[14:17], v[72:75]
	v_mfma_f32_16x16x32_bf16 v[80:83], v[84:87], v[14:17], v[80:83]
	v_pk_fma_f32 v[64:65], v[64:65], s[36:37], v[90:91] op_sel_hi:[1,0,1]
	v_pk_fma_f32 v[66:67], v[66:67], s[36:37], v[92:93] op_sel_hi:[1,0,1]
	v_pk_fma_f32 v[68:69], v[68:69], s[36:37], v[94:95] op_sel_hi:[1,0,1]
	v_pk_fma_f32 v[70:71], v[70:71], s[36:37], v[96:97] op_sel_hi:[1,0,1]
	s_nop 3
	v_pk_fma_f32 v[72:73], v[72:73], s[36:37], v[98:99] op_sel_hi:[1,0,1]
	v_pk_fma_f32 v[74:75], v[74:75], s[36:37], v[100:101] op_sel_hi:[1,0,1]
	v_pk_fma_f32 v[80:81], v[80:81], s[36:37], v[154:155] op_sel_hi:[1,0,1]
	v_pk_fma_f32 v[82:83], v[82:83], s[36:37], v[156:157] op_sel_hi:[1,0,1]
	v_max3_f32 v76, v64, v65, v66
	v_max3_f32 v76, v76, v67, v68
	v_max3_f32 v76, v76, v69, v70
	v_max3_f32 v76, v76, v71, v72
	v_max3_f32 v76, v76, v73, v74
	v_max3_f32 v76, v76, v75, v80
	v_max3_f32 v76, v76, v81, v82
	v_max3_f32 v76, v76, v83, s29
	v_mov_b32_e32 v77, v76
	s_nop 1
	v_permlane16_swap_b32_e32 v76, v77
	v_max_f32_e32 v76, v76, v77
	v_mov_b32_e32 v77, v76
	s_nop 1
	v_permlane32_swap_b32_e32 v76, v77
	v_max_f32_e32 v76, v76, v77
	v_cndmask_b32_e64 v76, v148, v76, s[42:43]
	v_max_f32_e32 v77, v161, v76
	v_sub_f32_e32 v0, v161, v77
	v_exp_f32_e32 v0, v0
	v_cndmask_b32_e64 v78, v209, v77, s[42:43]
	v_mov_b32_e32 v161, v77
	v_pk_mul_f32 v[32:33], v[32:33], v[0:1] op_sel_hi:[1,0]
	v_pk_mul_f32 v[30:31], v[30:31], v[0:1] op_sel_hi:[1,0]
	v_pk_mul_f32 v[28:29], v[28:29], v[0:1] op_sel_hi:[1,0]
	v_pk_mul_f32 v[26:27], v[26:27], v[0:1] op_sel_hi:[1,0]
	v_pk_mul_f32 v[24:25], v[24:25], v[0:1] op_sel_hi:[1,0]
	v_pk_mul_f32 v[22:23], v[22:23], v[0:1] op_sel_hi:[1,0]
	v_pk_mul_f32 v[20:21], v[20:21], v[0:1] op_sel_hi:[1,0]
	v_pk_mul_f32 v[18:19], v[18:19], v[0:1] op_sel_hi:[1,0]
	v_pk_add_f32 v[64:65], v[64:65], v[78:79] op_sel_hi:[1,0] neg_lo:[0,1] neg_hi:[0,1]
	v_pk_add_f32 v[66:67], v[66:67], v[78:79] op_sel_hi:[1,0] neg_lo:[0,1] neg_hi:[0,1]
	v_pk_add_f32 v[68:69], v[68:69], v[78:79] op_sel_hi:[1,0] neg_lo:[0,1] neg_hi:[0,1]
	v_pk_add_f32 v[70:71], v[70:71], v[78:79] op_sel_hi:[1,0] neg_lo:[0,1] neg_hi:[0,1]
	v_pk_add_f32 v[72:73], v[72:73], v[78:79] op_sel_hi:[1,0] neg_lo:[0,1] neg_hi:[0,1]
	v_pk_add_f32 v[74:75], v[74:75], v[78:79] op_sel_hi:[1,0] neg_lo:[0,1] neg_hi:[0,1]
	v_pk_add_f32 v[80:81], v[80:81], v[78:79] op_sel_hi:[1,0] neg_lo:[0,1] neg_hi:[0,1]
	v_pk_add_f32 v[82:83], v[82:83], v[78:79] op_sel_hi:[1,0] neg_lo:[0,1] neg_hi:[0,1]
	v_exp_f32_e32 v64, v64
	v_exp_f32_e32 v65, v65
	v_exp_f32_e32 v66, v66
	v_exp_f32_e32 v67, v67
	v_exp_f32_e32 v68, v68
	v_exp_f32_e32 v69, v69
	v_exp_f32_e32 v70, v70
	v_exp_f32_e32 v71, v71
	v_exp_f32_e32 v72, v72
	v_exp_f32_e32 v73, v73
	v_exp_f32_e32 v74, v74
	v_exp_f32_e32 v75, v75
	v_exp_f32_e32 v80, v80
	v_exp_f32_e32 v81, v81
	v_exp_f32_e32 v82, v82
	v_exp_f32_e32 v83, v83
	s_nop 0
	v_pk_add_f32 v[84:85], v[64:65], v[66:67]
	v_pk_add_f32 v[86:87], v[68:69], v[70:71]
	v_pk_add_f32 v[76:77], v[72:73], v[74:75]
	v_pk_add_f32 v[78:79], v[80:81], v[82:83]
	v_pk_add_f32 v[84:85], v[84:85], v[86:87]
	v_pk_add_f32 v[76:77], v[76:77], v[78:79]
	s_nop 0
	v_pk_add_f32 v[84:85], v[84:85], v[76:77]
	s_nop 0
	v_add_f32_e32 v84, v84, v85
	v_fma_f32 v145, v145, v0, v84
	v_cvt_pk_bf16_f32 v67, v66, v67
	v_cvt_pk_bf16_f32 v66, v64, v65
	v_cvt_pk_bf16_f32 v68, v68, v69
	v_cvt_pk_bf16_f32 v69, v70, v71
	v_cvt_pk_bf16_f32 v62, v72, v73
	v_cvt_pk_bf16_f32 v63, v74, v75
	v_cvt_pk_bf16_f32 v64, v80, v81
	v_cvt_pk_bf16_f32 v65, v82, v83
	s_branch .LBB0_446

.LBB0_439:
	s_andn2_b64 vcc, exec, s[6:7]
	s_cbranch_vccnz .LBB0_448
	v_and_b32_e32 v0, 1, v164
	v_cmp_eq_u32_e64 s[42:43], 1, v0
	v_and_b32_e32 v0, 1, v162
	v_cmp_eq_u32_e64 s[44:45], 1, v0
	s_or_b64 s[6:7], s[44:45], s[42:43]
	v_cndmask_b32_e64 v54, 0, 1, s[6:7]
	v_cmp_ne_u32_e32 vcc, 0, v54
	s_cbranch_vccz .Lsel_fast
	v_add_u32_e32 v54, s13, v196
	v_cmp_ne_u32_e32 vcc, 0, v0
	v_add_u32_e32 v62, v54, v194
	v_add_u32_e32 v0, v54, v195
	s_cbranch_vccz .LBB0_444
	ds_read_b128 v[54:57], v62 offset:16384
	ds_read_b32 v80, v193
	ds_read_b128 v[58:61], v62 offset:18432
	ds_read_b128 v[64:67], v62 offset:20480
	ds_read_b128 v[68:71], v0 offset:16384
	ds_read_b128 v[72:75], v62 offset:22528
	s_waitcnt lgkmcnt(0)
	v_mfma_f32_16x16x32_bf16 v[54:57], v[54:57], v[2:5], 0
	v_mfma_f32_16x16x32_bf16 v[58:61], v[58:61], v[2:5], 0
	v_mfma_f32_16x16x32_bf16 v[54:57], v[68:71], v[6:9], v[54:57]
	ds_read_b128 v[68:71], v0 offset:18432
	ds_read_b128 v[76:79], v0 offset:20480
	v_mfma_f32_16x16x32_bf16 v[64:67], v[64:67], v[2:5], 0
	v_mfma_f32_16x16x32_bf16 v[84:87], v[72:75], v[2:5], 0
	s_waitcnt lgkmcnt(0)
	v_mfma_f32_16x16x32_bf16 v[58:61], v[68:71], v[6:9], v[58:61]
	ds_read_b128 v[68:71], v0 offset:22528
	v_mfma_f32_16x16x32_bf16 v[64:67], v[76:79], v[6:9], v[64:67]
	s_waitcnt lgkmcnt(0)
	v_mfma_f32_16x16x32_bf16 v[84:87], v[68:71], v[6:9], v[84:87]
	v_max3_f32 v63, v54, v55, v56
	s_nop 2
	v_max3_f32 v63, v63, v57, v58
	v_max3_f32 v63, v63, v59, v60
	v_max3_f32 v63, v63, v61, v64
	v_max3_f32 v63, v63, v65, v66
	v_max3_f32 v63, v63, v67, v84
	v_max3_f32 v63, v63, v85, v86
	v_max_f32_e32 v63, v63, v87
	v_mov_b32_e32 v68, v63
	s_nop 1
	v_permlane16_swap_b32_e32 v63, v68
	v_max_f32_e32 v63, v63, v68
	v_mov_b32_e32 v68, v63
	s_nop 1
	v_permlane32_swap_b32_e32 v63, v68
	v_max_f32_e32 v63, v63, v68
	v_fma_f32 v63, v63, s36, v80
	v_max_f32_e32 v63, s29, v63
	v_cndmask_b32_e64 v63, v148, v63, s[44:45]
	v_max_f32_e32 v68, v160, v63
	v_sub_f32_e32 v69, v160, v68
	v_exp_f32_e32 v70, v69
	v_cndmask_b32_e64 v63, v209, v68, s[44:45]
	v_mov_b32_e32 v160, v68
	v_sub_f32_e32 v82, v80, v63
	v_pk_mul_f32 v[36:37], v[36:37], v[70:71] op_sel_hi:[1,0]
	v_pk_mul_f32 v[34:35], v[34:35], v[70:71] op_sel_hi:[1,0]
	v_pk_mul_f32 v[48:49], v[48:49], v[70:71] op_sel_hi:[1,0]
	v_pk_mul_f32 v[46:47], v[46:47], v[70:71] op_sel_hi:[1,0]
	v_pk_mul_f32 v[44:45], v[44:45], v[70:71] op_sel_hi:[1,0]
	v_pk_mul_f32 v[42:43], v[42:43], v[70:71] op_sel_hi:[1,0]
	v_pk_mul_f32 v[52:53], v[52:53], v[70:71] op_sel_hi:[1,0]
	v_pk_mul_f32 v[50:51], v[50:51], v[70:71] op_sel_hi:[1,0]
	v_pk_fma_f32 v[54:55], v[54:55], s[36:37], v[82:83] op_sel_hi:[1,0,0]
	v_pk_fma_f32 v[56:57], v[56:57], s[36:37], v[82:83] op_sel_hi:[1,0,0]
	v_pk_fma_f32 v[58:59], v[58:59], s[36:37], v[82:83] op_sel_hi:[1,0,0]
	v_pk_fma_f32 v[60:61], v[60:61], s[36:37], v[82:83] op_sel_hi:[1,0,0]
	v_pk_fma_f32 v[64:65], v[64:65], s[36:37], v[82:83] op_sel_hi:[1,0,0]
	v_pk_fma_f32 v[66:67], v[66:67], s[36:37], v[82:83] op_sel_hi:[1,0,0]
	v_pk_fma_f32 v[84:85], v[84:85], s[36:37], v[82:83] op_sel_hi:[1,0,0]
	v_pk_fma_f32 v[86:87], v[86:87], s[36:37], v[82:83] op_sel_hi:[1,0,0]
	v_exp_f32_e32 v54, v54
	v_exp_f32_e32 v55, v55
	v_exp_f32_e32 v56, v56
	v_exp_f32_e32 v57, v57
	v_exp_f32_e32 v58, v58
	v_exp_f32_e32 v59, v59
	v_exp_f32_e32 v60, v60
	v_exp_f32_e32 v61, v61
	v_exp_f32_e32 v64, v64
	v_exp_f32_e32 v65, v65
	v_exp_f32_e32 v66, v66
	v_exp_f32_e32 v67, v67
	v_exp_f32_e32 v84, v84
	v_exp_f32_e32 v85, v85
	v_exp_f32_e32 v86, v86
	v_exp_f32_e32 v87, v87
	s_nop 0
	v_pk_add_f32 v[72:73], v[54:55], v[56:57]
	v_pk_add_f32 v[74:75], v[58:59], v[60:61]
	v_pk_add_f32 v[76:77], v[64:65], v[66:67]
	v_pk_add_f32 v[78:79], v[84:85], v[86:87]
	v_pk_add_f32 v[72:73], v[72:73], v[74:75]
	v_pk_add_f32 v[76:77], v[76:77], v[78:79]
	s_nop 0
	v_pk_add_f32 v[72:73], v[72:73], v[76:77]
	s_nop 0
	v_add_f32_e32 v72, v72, v73
	v_fma_f32 v144, v144, v70, v72
	v_cvt_pk_bf16_f32 v61, v60, v61
	v_cvt_pk_bf16_f32 v60, v58, v59
	v_cvt_pk_bf16_f32 v59, v56, v57
	v_cvt_pk_bf16_f32 v58, v54, v55
	v_cvt_pk_bf16_f32 v54, v64, v65
	v_cvt_pk_bf16_f32 v55, v66, v67
	v_cvt_pk_bf16_f32 v56, v84, v85
	v_cvt_pk_bf16_f32 v57, v86, v87
	v_cndmask_b32_e64 v63, 0, 1, s[42:43]
	v_cmp_ne_u32_e32 vcc, 0, v63
	s_cbranch_vccz .LBB0_445
.LBB0_443:
	ds_read_b128 v[64:67], v62 offset:16384
	ds_read_b128 v[68:71], v62 offset:18432
	ds_read_b128 v[72:75], v0 offset:16384
	ds_read_b128 v[76:79], v0 offset:18432
	s_waitcnt lgkmcnt(0)
	v_mfma_f32_16x16x32_bf16 v[64:67], v[64:67], v[10:13], 0
	v_mfma_f32_16x16x32_bf16 v[68:71], v[68:71], v[10:13], 0
	v_mfma_f32_16x16x32_bf16 v[64:67], v[72:75], v[14:17], v[64:67]
	ds_read_b128 v[72:75], v62 offset:20480
	v_mfma_f32_16x16x32_bf16 v[68:71], v[76:79], v[14:17], v[68:71]
	ds_read_b128 v[76:79], v0 offset:20480
	ds_read_b128 v[80:83], v62 offset:22528
	ds_read_b32 v88, v193
	ds_read_b128 v[84:87], v0 offset:22528
	s_waitcnt lgkmcnt(0)
	v_mfma_f32_16x16x32_bf16 v[72:75], v[72:75], v[10:13], 0
	v_mfma_f32_16x16x32_bf16 v[80:83], v[80:83], v[10:13], 0
	v_mfma_f32_16x16x32_bf16 v[72:75], v[76:79], v[14:17], v[72:75]
	v_mfma_f32_16x16x32_bf16 v[80:83], v[84:87], v[14:17], v[80:83]
	v_max3_f32 v76, v64, v65, v66
	v_max3_f32 v76, v76, v67, v68
	v_max3_f32 v76, v76, v69, v70
	v_max_f32_e32 v76, v76, v71
	s_nop 3
	v_max3_f32 v76, v76, v72, v73
	v_max3_f32 v76, v76, v74, v75
	v_max3_f32 v76, v76, v80, v81
	v_max3_f32 v76, v76, v82, v83
	v_mov_b32_e32 v77, v76
	s_nop 1
	v_permlane16_swap_b32_e32 v76, v77
	v_max_f32_e32 v76, v76, v77
	v_mov_b32_e32 v77, v76
	s_nop 1
	v_permlane32_swap_b32_e32 v76, v77
	v_max_f32_e32 v76, v76, v77
	v_fma_f32 v76, v76, s36, v88
	v_max_f32_e32 v76, s29, v76
	v_cndmask_b32_e64 v76, v148, v76, s[42:43]
	v_max_f32_e32 v77, v161, v76
	v_sub_f32_e32 v0, v161, v77
	v_exp_f32_e32 v0, v0
	v_cndmask_b32_e64 v78, v209, v77, s[42:43]
	v_mov_b32_e32 v161, v77
	v_sub_f32_e32 v78, v88, v78
	v_pk_mul_f32 v[32:33], v[32:33], v[0:1] op_sel_hi:[1,0]
	v_pk_mul_f32 v[30:31], v[30:31], v[0:1] op_sel_hi:[1,0]
	v_pk_mul_f32 v[28:29], v[28:29], v[0:1] op_sel_hi:[1,0]
	v_pk_mul_f32 v[26:27], v[26:27], v[0:1] op_sel_hi:[1,0]
	v_pk_mul_f32 v[24:25], v[24:25], v[0:1] op_sel_hi:[1,0]
	v_pk_mul_f32 v[22:23], v[22:23], v[0:1] op_sel_hi:[1,0]
	v_pk_mul_f32 v[20:21], v[20:21], v[0:1] op_sel_hi:[1,0]
	v_pk_mul_f32 v[18:19], v[18:19], v[0:1] op_sel_hi:[1,0]
	v_pk_fma_f32 v[64:65], v[64:65], s[36:37], v[78:79] op_sel_hi:[1,0,0]
	v_pk_fma_f32 v[66:67], v[66:67], s[36:37], v[78:79] op_sel_hi:[1,0,0]
	v_pk_fma_f32 v[68:69], v[68:69], s[36:37], v[78:79] op_sel_hi:[1,0,0]
	v_pk_fma_f32 v[70:71], v[70:71], s[36:37], v[78:79] op_sel_hi:[1,0,0]
	v_pk_fma_f32 v[72:73], v[72:73], s[36:37], v[78:79] op_sel_hi:[1,0,0]
	v_pk_fma_f32 v[74:75], v[74:75], s[36:37], v[78:79] op_sel_hi:[1,0,0]
	v_pk_fma_f32 v[80:81], v[80:81], s[36:37], v[78:79] op_sel_hi:[1,0,0]
	v_pk_fma_f32 v[82:83], v[82:83], s[36:37], v[78:79] op_sel_hi:[1,0,0]
	v_exp_f32_e32 v64, v64
	v_exp_f32_e32 v65, v65
	v_exp_f32_e32 v66, v66
	v_exp_f32_e32 v67, v67
	v_exp_f32_e32 v68, v68
	v_exp_f32_e32 v69, v69
	v_exp_f32_e32 v70, v70
	v_exp_f32_e32 v71, v71
	v_exp_f32_e32 v72, v72
	v_exp_f32_e32 v73, v73
	v_exp_f32_e32 v74, v74
	v_exp_f32_e32 v75, v75
	v_exp_f32_e32 v80, v80
	v_exp_f32_e32 v81, v81
	v_exp_f32_e32 v82, v82
	v_exp_f32_e32 v83, v83
	s_nop 0
	v_pk_add_f32 v[84:85], v[64:65], v[66:67]
	v_pk_add_f32 v[86:87], v[68:69], v[70:71]
	v_pk_add_f32 v[76:77], v[72:73], v[74:75]
	v_pk_add_f32 v[78:79], v[80:81], v[82:83]
	v_pk_add_f32 v[84:85], v[84:85], v[86:87]
	v_pk_add_f32 v[76:77], v[76:77], v[78:79]
	s_nop 0
	v_pk_add_f32 v[84:85], v[84:85], v[76:77]
	s_nop 0
	v_add_f32_e32 v84, v84, v85
	v_fma_f32 v145, v145, v0, v84
	v_cvt_pk_bf16_f32 v67, v66, v67
	v_cvt_pk_bf16_f32 v66, v64, v65
	v_cvt_pk_bf16_f32 v68, v68, v69
	v_cvt_pk_bf16_f32 v69, v70, v71
	v_cvt_pk_bf16_f32 v62, v72, v73
	v_cvt_pk_bf16_f32 v63, v74, v75
	v_cvt_pk_bf16_f32 v64, v80, v81
	v_cvt_pk_bf16_f32 v65, v82, v83
	s_branch .LBB0_446

	.amdhsa_kernel _Z8mega_fwd6Params
		.amdhsa_group_segment_fixed_size 0
		.amdhsa_private_segment_fixed_size 0
		.amdhsa_kernarg_size 416
		.amdhsa_user_sgpr_count 2
		.amdhsa_user_sgpr_dispatch_ptr 0
		.amdhsa_user_sgpr_queue_ptr 0
		.amdhsa_user_sgpr_kernarg_segment_ptr 1
		.amdhsa_user_sgpr_dispatch_id 0
		.amdhsa_user_sgpr_kernarg_preload_length 0
		.amdhsa_user_sgpr_kernarg_preload_offset 0
		.amdhsa_user_sgpr_private_segment_size 0
		.amdhsa_uses_dynamic_stack 0
		.amdhsa_enable_private_segment 0
		.amdhsa_system_sgpr_workgroup_id_x 1
		.amdhsa_system_sgpr_workgroup_id_y 0
		.amdhsa_system_sgpr_workgroup_id_z 0
		.amdhsa_system_sgpr_workgroup_info 0
		.amdhsa_system_vgpr_workitem_id 2
		.amdhsa_next_free_vgpr 256
		.amdhsa_next_free_sgpr 102
		.amdhsa_accum_offset 256
		.amdhsa_reserve_vcc 1
		.amdhsa_float_round_mode_32 0
		.amdhsa_float_round_mode_16_64 0
		.amdhsa_float_denorm_mode_32 3
		.amdhsa_float_denorm_mode_16_64 3
		.amdhsa_dx10_clamp 1
		.amdhsa_ieee_mode 1
		.amdhsa_fp16_overflow 0
		.amdhsa_tg_split 0
		.amdhsa_exception_fp_ieee_invalid_op 0
		.amdhsa_exception_fp_denorm_src 0
		.amdhsa_exception_fp_ieee_div_zero 0
		.amdhsa_exception_fp_ieee_overflow 0
		.amdhsa_exception_fp_ieee_underflow 0
		.amdhsa_exception_fp_ieee_inexact 0
		.amdhsa_exception_int_div_zero 0
	.end_amdhsa_kernel

amdhsa.kernels:
  - .agpr_count:     0
    .args:
      - .offset:         0
        .size:           160
        .value_kind:     by_value
      - .offset:         160
        .size:           4
        .value_kind:     hidden_block_count_x
      - .offset:         164
        .size:           4
        .value_kind:     hidden_block_count_y
      - .offset:         168
        .size:           4
        .value_kind:     hidden_block_count_z
      - .offset:         172
        .size:           2
        .value_kind:     hidden_group_size_x
      - .offset:         174
        .size:           2
        .value_kind:     hidden_group_size_y
      - .offset:         176
        .size:           2
        .value_kind:     hidden_group_size_z
      - .offset:         178
        .size:           2
        .value_kind:     hidden_remainder_x
      - .offset:         180
        .size:           2
        .value_kind:     hidden_remainder_y
      - .offset:         182
        .size:           2
        .value_kind:     hidden_remainder_z
      - .offset:         200
        .size:           8
        .value_kind:     hidden_global_offset_x
      - .offset:         208
        .size:           8
        .value_kind:     hidden_global_offset_y
      - .offset:         216
        .size:           8
        .value_kind:     hidden_global_offset_z
      - .offset:         224
        .size:           2
        .value_kind:     hidden_grid_dims
      - .offset:         248
        .size:           8
        .value_kind:     hidden_multigrid_sync_arg
      - .offset:         280
        .size:           4
        .value_kind:     hidden_dynamic_lds_size
    .group_segment_fixed_size: 0
    .kernarg_segment_align: 8
    .kernarg_segment_size: 416
    .language:       OpenCL C
    .language_version:
      - 2
      - 0
    .max_flat_workgroup_size: 512
    .name:           _Z8mega_fwd6Params
    .private_segment_fixed_size: 0
    .sgpr_count:     108
    .sgpr_spill_count: 165
    .symbol:         _Z8mega_fwd6Params.kd
    .uniform_work_group_size: 1
    .uses_dynamic_stack: false
    .vgpr_count:     256
    .vgpr_spill_count: 0
    .wavefront_size: 64
